# K-loop: skip the first two vmcnt(8) waits of a tile's first K-iteration when an epilogue preceded (its vmcnt(0) already drained the prefetches), so epilogue stores drain under the first MFMA blocks
# baseline (speedup 1.0000x reference)
; __global__ void __launch_bounds__(512, 2) fwd_kernel(Params p) {
;     ...
;     for (int ph = p.ph_lo; ph < p.ph_hi; ++ph) {
;         if (ph > p.ph_lo) { if (ph == p.ph_lo + 1) cg::this_grid().sync(); else xcd_barrier(bar); }
;         int tid = threadIdx.x; asm volatile("" : "+v"(tid));
;         if (ph == 0) {
;             for (int e = blockIdx.x * 512 + tid; e < 12 * D; e += gridDim.x * 512) ((float*)(p.ws + WS_NG))[e] = p.norm_g[e];
;             phase_mod(p, lds, tid); continue; }
;         const int l = ph < 2 ? 0 : (ph - 2) / 8, s = ph < 2 ? 0 : (ph - 2) % 8 + 1;
;         float* ssq_all = (float*)(p.ws + WS_SSQ);
;         const float* shw_all = (const float*)(p.ws + WS_SHW);
;         if (s == 0) {
;             phase_shw(p, lds, tid); asm volatile("" : "+v"(tid)); phase_weights_a0(p, lds, tid); asm volatile("" : "+v"(tid)); phase_norm_first(p, tid);
;         }
;         else if (s == 4) phase_mixer(p, l, lds, tid);
;         else if (s == 5) phase_combine(p, l, tid);
;         else if (s == 1 || s == 7) {
.LBB0_76:
.LBB0_77:
	s_mov_b32 s100, 0
	v_mov_b32_e32 v174, v222
	s_cmp_lg_u32 s38, 0
	s_cbranch_scc0 .LBB0_104
	s_add_i32 s1, s38, 6
	s_add_i32 s0, s38, -2
	s_and_b32 s1, s1, 7
	s_lshr_b32 s0, s0, 3
	s_add_i32 s1, s1, 1
	s_cmp_lt_i32 s38, 2
	s_cselect_b32 s96, 0, s1
	s_cselect_b32 s28, 0, s0
	s_mov_b64 s[40:41], -1
	s_mov_b64 s[92:93], 0
	s_cmp_lt_i32 s96, 4
	s_mov_b64 s[34:35], 0
	s_mov_b64 s[36:37], 0
	s_cbranch_scc1 .LBB0_181
	s_cmp_gt_i32 s96, 4
	s_cbranch_scc0 .LBB0_89
	v_readlane_b32 s10, v254, 13
	s_cmp_gt_i32 s96, 6
	v_readlane_b32 s11, v254, 14
	s_cbranch_scc0 .LBB0_82
	s_cmp_lg_u32 s96, 7
	s_mov_b64 s[40:41], 0
	s_mov_b64 s[34:35], -1
	s_cselect_b64 s[36:37], -1, 0

; #define PG8_STAGE(bufoff, gbase, voff) do { _Pragma("unroll") for (int _i = 0; _i < 2; ++_i) \
;         __builtin_amdgcn_global_load_lds((const unsigned*)((const char*)(gbase) + (voff)[_i]), (PG8_LAS unsigned*)(lds + (bufoff) + ldsw + _i * 8192), 16, 0, 0); } while (0)
; #define PG8_LDA(dst, b, h) do { _Pragma("unroll") for (int m = 0; m < 4; ++m) _Pragma("unroll") for (int k = 0; k < 2; ++k) dst[m][k] = *(const PG8_LAS bf16x8*)(lds + PG8_SA(b, h) + aoff + m * 2048 + k * 1024); } while (0)
; #define PG8_LDB(dst, b, h) do { _Pragma("unroll") for (int n = 0; n < 2; ++n) _Pragma("unroll") for (int k = 0; k < 2; ++k) dst[n][k] = *(const PG8_LAS bf16x8*)(lds + PG8_SB(b, h) + boff + n * 2048 + k * 1024); } while (0)
; #define PG8_MMA(ai, bj, At, Bt) do { __builtin_amdgcn_s_setprio(1); _Pragma("unroll") for (int m = 0; m < 4; ++m) _Pragma("unroll") for (int n = 0; n < 2; ++n) _Pragma("unroll") for (int k = 0; k < 2; ++k) \
;         acc[ai][bj][m][n] = __builtin_amdgcn_mfma_f32_16x16x32_bf16(Bt[n][k], At[m][k], acc[ai][bj][m][n], 0, 0, 0); __builtin_amdgcn_s_setprio(0); } while (0)
; #define PG8_WAIT_V(n) asm volatile("s_waitcnt vmcnt(" #n ")" ::: "memory")
; #define PG8_BAR __builtin_amdgcn_s_barrier()
; template <class Epi, class Sched, bool ALIGN_EPI = false, bool SP2 = false>
; __device__ __forceinline__ void gemm_phase(PG8_LAS unsigned char* lds, const Gemm g, const Sched& S, const Epi& E, const int tid_in) {
;     ...
;         for (int t = 0; t < nt; t += 2) {
;             const bool last = (t == nt - 2);
;             const char* a1 = cA + (size_t)(t + 1) * kstep;
;             const char* a2 = last ? nA : cA + (size_t)(t + 2) * kstep; const char* b2 = last ? nB : cB + (size_t)(t + 2) * kstep;
;             const char* a3 = a2 + kstep; const char* b3 = b2 + kstep;
;             if (last && has_next) S.a_ready(nxt);
;             if constexpr (SP2) {
;             PG8_LDB(B0, 0, 0); PG8_LDB(B1, 0, 1); PG8_SCHED; PG8_LDA(At, 0, 0); PG8_STAGE(PG8_SA(1, 1), a1 + hstep, voffA);
;             PG8_WAIT_V(8); PG8_WAIT_L(0); PG8_BAR; PG8_MMA(0, 0, At, B0); PG8_MMA(0, 1, At, B1); PG8_BAR; PG8_SCHED;
;             PG8_LDA(At, 0, 1); PG8_STAGE(PG8_SB(0, 0), b2, voffB); PG8_STAGE(PG8_SB(0, 1), b2 + hstep, voffB); PG8_STAGE(PG8_SA(0, 0), a2, voffA);
;             PG8_WAIT_V(8); PG8_WAIT_L(0); PG8_BAR; PG8_MMA(1, 0, At, B0); PG8_MMA(1, 1, At, B1); PG8_BAR; PG8_SCHED;
.LBB0_197:
	s_add_u32 s51, s40, 0xfffc0080
	s_addc_u32 s56, s41, -1
	s_add_i32 s88, 0, 0x10000
	s_cmp_eq_u32 s49, 12
	s_cselect_b32 s59, s9, s56
	s_cselect_b32 s58, s16, s51
	s_cselect_b32 s57, s17, s39
	s_cselect_b32 s56, s20, s21
	s_add_i32 s51, 0, 0x14000
	v_add_u32_e32 v44, s88, v178
	v_add_u32_e32 v158, s51, v178
	ds_read_b128 v[24:27], v44
	ds_read_b128 v[28:31], v44 offset:1024
	ds_read_b128 v[40:43], v44 offset:2048
	ds_read_b128 v[44:47], v44 offset:3072
	ds_read_b128 v[154:157], v158
	ds_read_b128 v[182:185], v158 offset:1024
	ds_read_b128 v[186:189], v158 offset:2048
	ds_read_b128 v[190:193], v158 offset:3072
	v_lshl_add_u64 v[158:159], s[40:41], 0, v[150:151]
	s_add_i32 m0, s60, 0xc000
	ds_read_b128 v[194:197], v180
	ds_read_b128 v[198:201], v180 offset:1024
	ds_read_b128 v[202:205], v180 offset:2048
	ds_read_b128 v[206:209], v180 offset:3072
	ds_read_b128 v[210:213], v180 offset:4096
	ds_read_b128 v[214:217], v180 offset:5120
	ds_read_b128 v[218:221], v180 offset:6144
	ds_read_b128 v[238:241], v180 offset:7168
	global_load_lds_dwordx4 v[158:159], off
	v_lshl_add_u64 v[158:159], s[40:41], 0, v[152:153]
	s_add_i32 m0, s60, 0xe000
	s_nop 0
	global_load_lds_dwordx4 v[158:159], off
	s_cmp_eq_u32 s49, 0
	s_cselect_b32 s101, s100, 0
	s_cmp_lg_u32 s101, 0
	s_cbranch_scc1 .Lskipw_p_0
	s_waitcnt vmcnt(8)
.Lskipw_p_0:
	s_waitcnt lgkmcnt(0)
	s_barrier
	s_setprio 1
	s_waitcnt lgkmcnt(0)
	v_mfma_f32_16x16x32_bf16 v[140:143], v[24:27], v[194:197], v[140:143]
	v_mfma_f32_16x16x32_bf16 v[136:139], v[40:43], v[194:197], v[136:139]
	v_mfma_f32_16x16x32_bf16 v[124:127], v[24:27], v[202:205], v[124:127]
	v_mfma_f32_16x16x32_bf16 v[120:123], v[40:43], v[202:205], v[120:123]
	v_mfma_f32_16x16x32_bf16 v[108:111], v[24:27], v[210:213], v[108:111]
	v_mfma_f32_16x16x32_bf16 v[104:107], v[40:43], v[210:213], v[104:107]
	v_mfma_f32_16x16x32_bf16 v[92:95], v[24:27], v[218:221], v[92:95]
	v_mfma_f32_16x16x32_bf16 v[88:91], v[40:43], v[218:221], v[88:91]
	v_mfma_f32_16x16x32_bf16 v[140:143], v[28:31], v[198:201], v[140:143]
	v_mfma_f32_16x16x32_bf16 v[136:139], v[44:47], v[198:201], v[136:139]
	v_mfma_f32_16x16x32_bf16 v[124:127], v[28:31], v[206:209], v[124:127]
	v_mfma_f32_16x16x32_bf16 v[120:123], v[44:47], v[206:209], v[120:123]
	v_mfma_f32_16x16x32_bf16 v[108:111], v[28:31], v[214:217], v[108:111]
	v_mfma_f32_16x16x32_bf16 v[104:107], v[44:47], v[214:217], v[104:107]
	v_mfma_f32_16x16x32_bf16 v[92:95], v[28:31], v[238:241], v[92:95]
	v_mfma_f32_16x16x32_bf16 v[88:91], v[44:47], v[238:241], v[88:91]
	s_setprio 0
	s_setprio 1
	v_mfma_f32_16x16x32_bf16 v[132:135], v[154:157], v[194:197], v[132:135]
	v_mfma_f32_16x16x32_bf16 v[128:131], v[186:189], v[194:197], v[128:131]
	v_mfma_f32_16x16x32_bf16 v[116:119], v[154:157], v[202:205], v[116:119]
	v_mfma_f32_16x16x32_bf16 v[112:115], v[186:189], v[202:205], v[112:115]
	v_mfma_f32_16x16x32_bf16 v[100:103], v[154:157], v[210:213], v[100:103]
	v_mfma_f32_16x16x32_bf16 v[96:99], v[186:189], v[210:213], v[96:99]
	v_mfma_f32_16x16x32_bf16 v[84:87], v[154:157], v[218:221], v[84:87]
	v_mfma_f32_16x16x32_bf16 v[80:83], v[186:189], v[218:221], v[80:83]
	v_mfma_f32_16x16x32_bf16 v[132:135], v[182:185], v[198:201], v[132:135]
	v_mfma_f32_16x16x32_bf16 v[128:131], v[190:193], v[198:201], v[128:131]
	v_mfma_f32_16x16x32_bf16 v[116:119], v[182:185], v[206:209], v[116:119]
	v_mfma_f32_16x16x32_bf16 v[112:115], v[190:193], v[206:209], v[112:115]
	v_mfma_f32_16x16x32_bf16 v[100:103], v[182:185], v[214:217], v[100:103]
	v_mfma_f32_16x16x32_bf16 v[96:99], v[190:193], v[214:217], v[96:99]
	v_mfma_f32_16x16x32_bf16 v[84:87], v[182:185], v[238:241], v[84:87]
	v_mfma_f32_16x16x32_bf16 v[80:83], v[190:193], v[238:241], v[80:83]
	s_setprio 0
	s_barrier
	s_add_i32 s88, s88, s29
	v_lshl_add_u64 v[158:159], s[56:57], 0, v[160:161]
	s_mov_b32 m0, s88
	ds_read_b128 v[194:197], v180 offset:16384
	ds_read_b128 v[198:201], v180 offset:17408
	ds_read_b128 v[202:205], v180 offset:18432
	ds_read_b128 v[206:209], v180 offset:19456
	ds_read_b128 v[210:213], v180 offset:20480
	ds_read_b128 v[214:217], v180 offset:21504
	ds_read_b128 v[218:221], v180 offset:22528
	ds_read_b128 v[238:241], v180 offset:23552
	global_load_lds_dwordx4 v[158:159], off
	s_add_i32 m0, s88, 0x2000
	s_add_u32 s88, s56, 0x40000
	v_lshl_add_u64 v[176:177], s[56:57], 0, v[144:145]
	s_addc_u32 s89, s57, 0
	s_add_i32 s51, s51, s29
	global_load_lds_dwordx4 v[176:177], off
	v_lshl_add_u64 v[242:243], s[88:89], 0, v[160:161]
	s_mov_b32 m0, s51
	v_lshl_add_u64 v[244:245], s[58:59], 0, v[146:147]
	global_load_lds_dwordx4 v[242:243], off
	v_lshl_add_u64 v[242:243], s[88:89], 0, v[144:145]
	s_add_i32 m0, s51, 0x2000
	s_nop 0
	global_load_lds_dwordx4 v[242:243], off
	v_lshl_add_u64 v[242:243], s[58:59], 0, v[148:149]
	s_mov_b32 m0, s60
	s_nop 0
	global_load_lds_dwordx4 v[242:243], off
	s_mov_b32 m0, s61
	s_nop 0
	global_load_lds_dwordx4 v[244:245], off
	s_cmp_eq_u32 s49, 0
	s_cselect_b32 s101, s100, 0
	s_cmp_lg_u32 s101, 0
	s_cbranch_scc1 .Lskipw_p_1
	s_waitcnt vmcnt(8)
; #define PG8_STAGE(bufoff, gbase, voff) do { _Pragma("unroll") for (int _i = 0; _i < 2; ++_i) \
;         __builtin_amdgcn_global_load_lds((const unsigned*)((const char*)(gbase) + (voff)[_i]), (PG8_LAS unsigned*)(lds + (bufoff) + ldsw + _i * 8192), 16, 0, 0); } while (0)
; #define PG8_LDA(dst, b, h) do { _Pragma("unroll") for (int m = 0; m < 4; ++m) _Pragma("unroll") for (int k = 0; k < 2; ++k) dst[m][k] = *(const PG8_LAS bf16x8*)(lds + PG8_SA(b, h) + aoff + m * 2048 + k * 1024); } while (0)
; #define PG8_LDB(dst, b, h) do { _Pragma("unroll") for (int n = 0; n < 2; ++n) _Pragma("unroll") for (int k = 0; k < 2; ++k) dst[n][k] = *(const PG8_LAS bf16x8*)(lds + PG8_SB(b, h) + boff + n * 2048 + k * 1024); } while (0)
; #define PG8_MMA(ai, bj, At, Bt) do { __builtin_amdgcn_s_setprio(1); _Pragma("unroll") for (int m = 0; m < 4; ++m) _Pragma("unroll") for (int n = 0; n < 2; ++n) _Pragma("unroll") for (int k = 0; k < 2; ++k) \
;         acc[ai][bj][m][n] = __builtin_amdgcn_mfma_f32_16x16x32_bf16(Bt[n][k], At[m][k], acc[ai][bj][m][n], 0, 0, 0); __builtin_amdgcn_s_setprio(0); } while (0)
; #define PG8_WAIT_V(n) asm volatile("s_waitcnt vmcnt(" #n ")" ::: "memory")
; #define PG8_WAIT_L(n) asm volatile("s_waitcnt lgkmcnt(" #n ")" ::: "memory")
; #define PG8_BAR __builtin_amdgcn_s_barrier()
; #define PG8_SCHED __builtin_amdgcn_sched_barrier(0)
; template <class Epi, class Sched, bool ALIGN_EPI = false, bool SP2 = false>
; __device__ __forceinline__ void gemm_phase(PG8_LAS unsigned char* lds, const Gemm g, const Sched& S, const Epi& E, const int tid_in) {
;     ...
;             PG8_WAIT_V(8); PG8_WAIT_L(0); PG8_BAR; PG8_MMA(1, 0, At, B0); PG8_MMA(1, 1, At, B1); PG8_BAR; PG8_SCHED;
;             PG8_LDB(B0, 1, 0); PG8_LDB(B1, 1, 1); PG8_SCHED; PG8_LDA(At, 1, 0); PG8_STAGE(PG8_SA(0, 1), a2 + hstep, voffA);
;             PG8_WAIT_V(8); PG8_WAIT_L(0); PG8_BAR; PG8_MMA(0, 0, At, B0); PG8_MMA(0, 1, At, B1); PG8_BAR; PG8_SCHED;
.Lskipw_p_1:
	s_waitcnt lgkmcnt(0)
	s_barrier
	s_setprio 1
	s_waitcnt lgkmcnt(0)
	v_mfma_f32_16x16x32_bf16 v[76:79], v[24:27], v[194:197], v[76:79]
	v_mfma_f32_16x16x32_bf16 v[72:75], v[40:43], v[194:197], v[72:75]
	v_mfma_f32_16x16x32_bf16 v[60:63], v[24:27], v[202:205], v[60:63]
	v_mfma_f32_16x16x32_bf16 v[56:59], v[40:43], v[202:205], v[56:59]
	v_mfma_f32_16x16x32_bf16 v[36:39], v[24:27], v[210:213], v[36:39]
	v_mfma_f32_16x16x32_bf16 v[32:35], v[40:43], v[210:213], v[32:35]
	v_mfma_f32_16x16x32_bf16 v[12:15], v[24:27], v[218:221], v[12:15]
	v_mfma_f32_16x16x32_bf16 v[8:11], v[40:43], v[218:221], v[8:11]
	v_mfma_f32_16x16x32_bf16 v[76:79], v[28:31], v[198:201], v[76:79]
	v_mfma_f32_16x16x32_bf16 v[72:75], v[44:47], v[198:201], v[72:75]
	v_mfma_f32_16x16x32_bf16 v[60:63], v[28:31], v[206:209], v[60:63]
	v_mfma_f32_16x16x32_bf16 v[56:59], v[44:47], v[206:209], v[56:59]
	v_mfma_f32_16x16x32_bf16 v[36:39], v[28:31], v[214:217], v[36:39]
	v_mfma_f32_16x16x32_bf16 v[32:35], v[44:47], v[214:217], v[32:35]
	v_mfma_f32_16x16x32_bf16 v[12:15], v[28:31], v[238:241], v[12:15]
	v_mfma_f32_16x16x32_bf16 v[8:11], v[44:47], v[238:241], v[8:11]
	s_setprio 0
	s_setprio 1
	v_mfma_f32_16x16x32_bf16 v[20:23], v[154:157], v[210:213], v[20:23]
	v_mfma_f32_16x16x32_bf16 v[16:19], v[186:189], v[210:213], v[16:19]
	v_mfma_f32_16x16x32_bf16 v[4:7], v[154:157], v[218:221], v[4:7]
	v_mfma_f32_16x16x32_bf16 v[0:3], v[186:189], v[218:221], v[0:3]
	v_mfma_f32_16x16x32_bf16 v[24:27], v[154:157], v[194:197], v[68:71]
	v_mfma_f32_16x16x32_bf16 v[28:31], v[186:189], v[194:197], v[64:67]
	v_mfma_f32_16x16x32_bf16 v[40:43], v[154:157], v[202:205], v[52:55]
	v_mfma_f32_16x16x32_bf16 v[44:47], v[186:189], v[202:205], v[48:51]
	v_mfma_f32_16x16x32_bf16 v[20:23], v[182:185], v[214:217], v[20:23]
	v_mfma_f32_16x16x32_bf16 v[16:19], v[190:193], v[214:217], v[16:19]
	v_mfma_f32_16x16x32_bf16 v[4:7], v[182:185], v[238:241], v[4:7]
	v_mfma_f32_16x16x32_bf16 v[0:3], v[190:193], v[238:241], v[0:3]
	v_mfma_f32_16x16x32_bf16 v[24:27], v[182:185], v[198:201], v[24:27]
	v_mfma_f32_16x16x32_bf16 v[28:31], v[190:193], v[198:201], v[28:31]
	v_mfma_f32_16x16x32_bf16 v[40:43], v[182:185], v[206:209], v[40:43]
	v_mfma_f32_16x16x32_bf16 v[44:47], v[190:193], v[206:209], v[44:47]
	s_setprio 0
	s_barrier
	s_add_i32 s51, 0, 0x18000
	s_add_i32 s88, 0, 0x1c000
	v_add_u32_e32 v68, s51, v178
	v_add_u32_e32 v181, s88, v178
	ds_read_b128 v[48:51], v68
	ds_read_b128 v[52:55], v68 offset:1024
	ds_read_b128 v[64:67], v68 offset:2048
	ds_read_b128 v[68:71], v68 offset:3072
	ds_read_b128 v[154:157], v181
	ds_read_b128 v[182:185], v181 offset:1024
	ds_read_b128 v[186:189], v181 offset:2048
	ds_read_b128 v[190:193], v181 offset:3072
	s_add_u32 s58, s58, 0x40000
	s_addc_u32 s59, s59, 0
	s_mov_b32 m0, s62
	v_lshl_add_u64 v[246:247], s[58:59], 0, v[148:149]
	ds_read_b128 v[194:197], v180 offset:32768
	ds_read_b128 v[198:201], v180 offset:33792
	ds_read_b128 v[202:205], v180 offset:34816
	ds_read_b128 v[206:209], v180 offset:35840
	ds_read_b128 v[210:213], v180 offset:36864
	ds_read_b128 v[214:217], v180 offset:37888
	ds_read_b128 v[218:221], v180 offset:38912
	ds_read_b128 v[238:241], v180 offset:39936
	global_load_lds_dwordx4 v[246:247], off
	v_lshl_add_u64 v[246:247], s[58:59], 0, v[146:147]
	s_mov_b32 m0, s63
	s_nop 0
	global_load_lds_dwordx4 v[246:247], off
	s_waitcnt vmcnt(8)
	s_waitcnt lgkmcnt(0)
	s_barrier
	s_setprio 1
	s_waitcnt lgkmcnt(0)
	v_mfma_f32_16x16x32_bf16 v[140:143], v[48:51], v[194:197], v[140:143]
	v_mfma_f32_16x16x32_bf16 v[136:139], v[64:67], v[194:197], v[136:139]
	v_mfma_f32_16x16x32_bf16 v[124:127], v[48:51], v[202:205], v[124:127]
	v_mfma_f32_16x16x32_bf16 v[120:123], v[64:67], v[202:205], v[120:123]
	v_mfma_f32_16x16x32_bf16 v[108:111], v[48:51], v[210:213], v[108:111]
	v_mfma_f32_16x16x32_bf16 v[104:107], v[64:67], v[210:213], v[104:107]
	v_mfma_f32_16x16x32_bf16 v[92:95], v[48:51], v[218:221], v[92:95]
	v_mfma_f32_16x16x32_bf16 v[88:91], v[64:67], v[218:221], v[88:91]
	v_mfma_f32_16x16x32_bf16 v[140:143], v[52:55], v[198:201], v[140:143]
	v_mfma_f32_16x16x32_bf16 v[136:139], v[68:71], v[198:201], v[136:139]
	v_mfma_f32_16x16x32_bf16 v[124:127], v[52:55], v[206:209], v[124:127]
	v_mfma_f32_16x16x32_bf16 v[120:123], v[68:71], v[206:209], v[120:123]
	v_mfma_f32_16x16x32_bf16 v[108:111], v[52:55], v[214:217], v[108:111]
	v_mfma_f32_16x16x32_bf16 v[104:107], v[68:71], v[214:217], v[104:107]
	v_mfma_f32_16x16x32_bf16 v[92:95], v[52:55], v[238:241], v[92:95]
	v_mfma_f32_16x16x32_bf16 v[88:91], v[68:71], v[238:241], v[88:91]
	s_setprio 0
	s_setprio 1
	v_mfma_f32_16x16x32_bf16 v[132:135], v[154:157], v[194:197], v[132:135]
	v_mfma_f32_16x16x32_bf16 v[128:131], v[186:189], v[194:197], v[128:131]
	v_mfma_f32_16x16x32_bf16 v[116:119], v[154:157], v[202:205], v[116:119]
	v_mfma_f32_16x16x32_bf16 v[112:115], v[186:189], v[202:205], v[112:115]
	v_mfma_f32_16x16x32_bf16 v[100:103], v[154:157], v[210:213], v[100:103]
	v_mfma_f32_16x16x32_bf16 v[96:99], v[186:189], v[210:213], v[96:99]
	v_mfma_f32_16x16x32_bf16 v[84:87], v[154:157], v[218:221], v[84:87]
	v_mfma_f32_16x16x32_bf16 v[80:83], v[186:189], v[218:221], v[80:83]
	v_mfma_f32_16x16x32_bf16 v[132:135], v[182:185], v[198:201], v[132:135]
	v_mfma_f32_16x16x32_bf16 v[128:131], v[190:193], v[198:201], v[128:131]
	v_mfma_f32_16x16x32_bf16 v[116:119], v[182:185], v[206:209], v[116:119]
	v_mfma_f32_16x16x32_bf16 v[112:115], v[190:193], v[206:209], v[112:115]
	v_mfma_f32_16x16x32_bf16 v[100:103], v[182:185], v[214:217], v[100:103]
	v_mfma_f32_16x16x32_bf16 v[96:99], v[190:193], v[214:217], v[96:99]
	v_mfma_f32_16x16x32_bf16 v[84:87], v[182:185], v[238:241], v[84:87]
	v_mfma_f32_16x16x32_bf16 v[80:83], v[190:193], v[238:241], v[80:83]
	s_setprio 0
	s_barrier
; #define PG8_STAGE(bufoff, gbase, voff) do { _Pragma("unroll") for (int _i = 0; _i < 2; ++_i) \
;         __builtin_amdgcn_global_load_lds((const unsigned*)((const char*)(gbase) + (voff)[_i]), (PG8_LAS unsigned*)(lds + (bufoff) + ldsw + _i * 8192), 16, 0, 0); } while (0)
; #define PG8_LDA(dst, b, h) do { _Pragma("unroll") for (int m = 0; m < 4; ++m) _Pragma("unroll") for (int k = 0; k < 2; ++k) dst[m][k] = *(const PG8_LAS bf16x8*)(lds + PG8_SA(b, h) + aoff + m * 2048 + k * 1024); } while (0)
; #define PG8_MMA(ai, bj, At, Bt) do { __builtin_amdgcn_s_setprio(1); _Pragma("unroll") for (int m = 0; m < 4; ++m) _Pragma("unroll") for (int n = 0; n < 2; ++n) _Pragma("unroll") for (int k = 0; k < 2; ++k) \
;         acc[ai][bj][m][n] = __builtin_amdgcn_mfma_f32_16x16x32_bf16(Bt[n][k], At[m][k], acc[ai][bj][m][n], 0, 0, 0); __builtin_amdgcn_s_setprio(0); } while (0)
; #define PG8_WAIT_V(n) asm volatile("s_waitcnt vmcnt(" #n ")" ::: "memory")
; #define PG8_WAIT_L(n) asm volatile("s_waitcnt lgkmcnt(" #n ")" ::: "memory")
; #define PG8_BAR __builtin_amdgcn_s_barrier()
; #define PG8_SCHED __builtin_amdgcn_sched_barrier(0)
; template <class Epi, class Sched, bool ALIGN_EPI = false, bool SP2 = false>
; __device__ __forceinline__ void gemm_phase(PG8_LAS unsigned char* lds, const Gemm g, const Sched& S, const Epi& E, const int tid_in) {
;     ...
;         for (int t = 0; t < nt; t += 2) {
;             const bool last = (t == nt - 2);
;             const char* a1 = cA + (size_t)(t + 1) * kstep;
;             const char* a2 = last ? nA : cA + (size_t)(t + 2) * kstep; const char* b2 = last ? nB : cB + (size_t)(t + 2) * kstep;
;             const char* a3 = a2 + kstep; const char* b3 = b2 + kstep;
;     ...
;             PG8_LDA(At, 1, 1); PG8_STAGE(PG8_SB(1, 0), b3, voffB); PG8_STAGE(PG8_SB(1, 1), b3 + hstep, voffB); PG8_STAGE(PG8_SA(1, 0), a3, voffA);
;             PG8_WAIT_V(8); PG8_WAIT_L(0); PG8_BAR; PG8_MMA(1, 0, At, B0); PG8_MMA(1, 1, At, B1); PG8_BAR; PG8_SCHED;
	s_add_i32 s51, s51, s29
	v_lshl_add_u64 v[158:159], v[158:159], 0, s[26:27]
	s_mov_b32 m0, s51
	ds_read_b128 v[194:197], v180 offset:49152
	ds_read_b128 v[198:201], v180 offset:50176
	ds_read_b128 v[202:205], v180 offset:51200
	ds_read_b128 v[206:209], v180 offset:52224
	ds_read_b128 v[210:213], v180 offset:53248
	ds_read_b128 v[214:217], v180 offset:54272
	ds_read_b128 v[218:221], v180 offset:55296
	ds_read_b128 v[238:241], v180 offset:56320
	global_load_lds_dwordx4 v[158:159], off
	s_add_i32 m0, s51, 0x2000
	s_add_u32 s56, s56, 0x40080
	v_lshl_add_u64 v[158:159], v[176:177], 0, s[26:27]
	s_addc_u32 s57, s57, 0
	s_add_i32 s51, s88, s29
	global_load_lds_dwordx4 v[158:159], off
	v_lshl_add_u64 v[158:159], s[56:57], 0, v[160:161]
	s_mov_b32 m0, s51
	s_nop 0
	global_load_lds_dwordx4 v[158:159], off
	v_lshl_add_u64 v[158:159], s[56:57], 0, v[144:145]
	s_add_i32 m0, s51, 0x2000
	s_nop 0
	global_load_lds_dwordx4 v[158:159], off
	v_lshl_add_u64 v[158:159], v[242:243], 0, s[26:27]
	s_mov_b32 m0, s84
	s_nop 0
	global_load_lds_dwordx4 v[158:159], off
	v_lshl_add_u64 v[158:159], v[244:245], 0, s[26:27]
	s_mov_b32 m0, s85
	s_nop 0
	global_load_lds_dwordx4 v[158:159], off
	s_waitcnt vmcnt(8)
	s_waitcnt lgkmcnt(0)
	s_barrier
	s_setprio 1
	s_waitcnt lgkmcnt(0)
	v_mfma_f32_16x16x32_bf16 v[76:79], v[48:51], v[194:197], v[76:79]
	v_mfma_f32_16x16x32_bf16 v[72:75], v[64:67], v[194:197], v[72:75]
	v_mfma_f32_16x16x32_bf16 v[60:63], v[48:51], v[202:205], v[60:63]
	v_mfma_f32_16x16x32_bf16 v[56:59], v[64:67], v[202:205], v[56:59]
	v_mfma_f32_16x16x32_bf16 v[36:39], v[48:51], v[210:213], v[36:39]
	v_mfma_f32_16x16x32_bf16 v[32:35], v[64:67], v[210:213], v[32:35]
	v_mfma_f32_16x16x32_bf16 v[12:15], v[48:51], v[218:221], v[12:15]
	v_mfma_f32_16x16x32_bf16 v[8:11], v[64:67], v[218:221], v[8:11]
	v_mfma_f32_16x16x32_bf16 v[76:79], v[52:55], v[198:201], v[76:79]
	v_mfma_f32_16x16x32_bf16 v[72:75], v[68:71], v[198:201], v[72:75]
	v_mfma_f32_16x16x32_bf16 v[60:63], v[52:55], v[206:209], v[60:63]
	v_mfma_f32_16x16x32_bf16 v[56:59], v[68:71], v[206:209], v[56:59]
	v_mfma_f32_16x16x32_bf16 v[36:39], v[52:55], v[214:217], v[36:39]
	v_mfma_f32_16x16x32_bf16 v[32:35], v[68:71], v[214:217], v[32:35]
	v_mfma_f32_16x16x32_bf16 v[12:15], v[52:55], v[238:241], v[12:15]
	v_mfma_f32_16x16x32_bf16 v[8:11], v[68:71], v[238:241], v[8:11]
	s_setprio 0
	s_setprio 1
	v_mfma_f32_16x16x32_bf16 v[24:27], v[154:157], v[194:197], v[24:27]
	v_mfma_f32_16x16x32_bf16 v[68:71], v[182:185], v[198:201], v[24:27]
	v_mfma_f32_16x16x32_bf16 v[24:27], v[186:189], v[194:197], v[28:31]
	v_mfma_f32_16x16x32_bf16 v[64:67], v[190:193], v[198:201], v[24:27]
	v_mfma_f32_16x16x32_bf16 v[24:27], v[154:157], v[202:205], v[40:43]
	v_mfma_f32_16x16x32_bf16 v[52:55], v[182:185], v[206:209], v[24:27]
	v_mfma_f32_16x16x32_bf16 v[24:27], v[186:189], v[202:205], v[44:47]
	v_mfma_f32_16x16x32_bf16 v[20:23], v[154:157], v[210:213], v[20:23]
	v_mfma_f32_16x16x32_bf16 v[16:19], v[186:189], v[210:213], v[16:19]
	v_mfma_f32_16x16x32_bf16 v[4:7], v[154:157], v[218:221], v[4:7]
	v_mfma_f32_16x16x32_bf16 v[0:3], v[186:189], v[218:221], v[0:3]
	v_mfma_f32_16x16x32_bf16 v[48:51], v[190:193], v[206:209], v[24:27]
	v_mfma_f32_16x16x32_bf16 v[20:23], v[182:185], v[214:217], v[20:23]
	v_mfma_f32_16x16x32_bf16 v[16:19], v[190:193], v[214:217], v[16:19]
	v_mfma_f32_16x16x32_bf16 v[4:7], v[182:185], v[238:241], v[4:7]
	v_mfma_f32_16x16x32_bf16 v[0:3], v[190:193], v[238:241], v[0:3]
	s_setprio 0
	s_barrier
	s_add_i32 s49, s49, 2
	s_add_u32 s40, s40, 0x100
	s_addc_u32 s41, s41, 0
	s_add_u32 s21, s21, 0x100
	s_addc_u32 s39, s39, 0
	s_cmp_gt_u32 s49, 13
	s_cbranch_scc0 .LBB0_197
	s_and_b64 vcc, exec, s[46:47]
	s_cbranch_vccz .LBB0_200
	s_barrier

; __device__ __forceinline__ unsigned cvt_pk_bf16(float lo, float hi) { unsigned r; asm volatile("v_cvt_pk_bf16_f32 %0, %1, %2" : "=v"(r) : "v"(lo), "v"(hi)); return r; }
; #define PG8_BAR __builtin_amdgcn_s_barrier()
; template <class Epi, class Sched, bool ALIGN_EPI = false, bool SP2 = false>
; __device__ __forceinline__ void gemm_phase(PG8_LAS unsigned char* lds, const Gemm g, const Sched& S, const Epi& E, const int tid_in) {
;     ...
;         if (!has_next) break;
; #pragma unroll
;         for (int a = 0; a < 2; ++a)
; #pragma unroll
;             for (int b = 0; b < 2; ++b)
; #pragma unroll
;                 for (int m = 0; m < 4; ++m)
; #pragma unroll
;                     for (int n = 0; n < 2; ++n) acc[a][b][m][n] = (f32x4){0.f, 0.f, 0.f, 0.f};
;         cur = nxt; cA = nA; cB = nB; ++ui;
;         if constexpr (ALIGN_EPI) { if (wr == 1) PG8_BAR; }
;     __device__ __forceinline__ void operator()(const f32x4 (&acc)[2][2][4][2], const Unit& u, int wr, int wc, int fr, int fq) const {
;     ...
;                     u32x4 w; w.x = cvt_pk_bf16(v0[0], v0[1]); w.y = cvt_pk_bf16(v0[2], v0[3]); w.z = cvt_pk_bf16(v1[0], v1[1]); w.w = cvt_pk_bf16(v1[2], v1[3]);
;                     *(u32x4*)(rowp + bj * HALF) = w; } }
.LBB0_296:
	s_andn2_b64 vcc, exec, s[42:43]
	s_mov_b64 s[40:41], -1
	s_mov_b32 s20, 0xffff
	v_cvt_pk_bf16_f32 v0, v10, v12
	v_cvt_pk_bf16_f32 v1, v14, v17
	v_cvt_pk_bf16_f32 v2, v11, v13
	v_cvt_pk_bf16_f32 v3, v15, v16
	global_store_dwordx4 v[8:9], v[0:3], off offset:256
	s_mov_b32 s100, 1
	s_cbranch_vccnz .LBB0_189
	s_andn2_b64 vcc, exec, s[30:31]
	s_cbranch_vccnz .LBB0_188
	s_barrier
	s_branch .LBB0_188

; #define PG8_STAGE(bufoff, gbase, voff) do { _Pragma("unroll") for (int _i = 0; _i < 2; ++_i) \
;         __builtin_amdgcn_global_load_lds((const unsigned*)((const char*)(gbase) + (voff)[_i]), (PG8_LAS unsigned*)(lds + (bufoff) + ldsw + _i * 8192), 16, 0, 0); } while (0)
; #define PG8_LDA(dst, b, h) do { _Pragma("unroll") for (int m = 0; m < 4; ++m) _Pragma("unroll") for (int k = 0; k < 2; ++k) dst[m][k] = *(const PG8_LAS bf16x8*)(lds + PG8_SA(b, h) + aoff + m * 2048 + k * 1024); } while (0)
; #define PG8_LDB(dst, b, h) do { _Pragma("unroll") for (int n = 0; n < 2; ++n) _Pragma("unroll") for (int k = 0; k < 2; ++k) dst[n][k] = *(const PG8_LAS bf16x8*)(lds + PG8_SB(b, h) + boff + n * 2048 + k * 1024); } while (0)
; #define PG8_MMA(ai, bj, At, Bt) do { __builtin_amdgcn_s_setprio(1); _Pragma("unroll") for (int m = 0; m < 4; ++m) _Pragma("unroll") for (int n = 0; n < 2; ++n) _Pragma("unroll") for (int k = 0; k < 2; ++k) \
;         acc[ai][bj][m][n] = __builtin_amdgcn_mfma_f32_16x16x32_bf16(Bt[n][k], At[m][k], acc[ai][bj][m][n], 0, 0, 0); __builtin_amdgcn_s_setprio(0); } while (0)
; #define PG8_WAIT_V(n) asm volatile("s_waitcnt vmcnt(" #n ")" ::: "memory")
; #define PG8_BAR __builtin_amdgcn_s_barrier()
; template <class Epi, class Sched, bool ALIGN_EPI = false, bool SP2 = false>
; __device__ __forceinline__ void gemm_phase(PG8_LAS unsigned char* lds, const Gemm g, const Sched& S, const Epi& E, const int tid_in) {
;     ...
;         for (int t = 0; t < nt; t += 2) {
;             const bool last = (t == nt - 2);
;             const char* a1 = cA + (size_t)(t + 1) * kstep;
;             const char* a2 = last ? nA : cA + (size_t)(t + 2) * kstep; const char* b2 = last ? nB : cB + (size_t)(t + 2) * kstep;
;             const char* a3 = a2 + kstep; const char* b3 = b2 + kstep;
;             if (last && has_next) S.a_ready(nxt);
;             if constexpr (SP2) {
;             PG8_LDB(B0, 0, 0); PG8_LDB(B1, 0, 1); PG8_SCHED; PG8_LDA(At, 0, 0); PG8_STAGE(PG8_SA(1, 1), a1 + hstep, voffA);
;             PG8_WAIT_V(8); PG8_WAIT_L(0); PG8_BAR; PG8_MMA(0, 0, At, B0); PG8_MMA(0, 1, At, B1); PG8_BAR; PG8_SCHED;
;             PG8_LDA(At, 0, 1); PG8_STAGE(PG8_SB(0, 0), b2, voffB); PG8_STAGE(PG8_SB(0, 1), b2 + hstep, voffB); PG8_STAGE(PG8_SA(0, 0), a2, voffA);
;             PG8_WAIT_V(8); PG8_WAIT_L(0); PG8_BAR; PG8_MMA(1, 0, At, B0); PG8_MMA(1, 1, At, B1); PG8_BAR; PG8_SCHED;
.LBB0_322:
	s_add_i32 s65, s46, 2
	s_add_u32 vcc_lo, s40, 0x80
	s_addc_u32 s47, s41, 0
	s_add_i32 s10, 0, 0x10000
	s_cmp_eq_u32 s93, s46
	s_cselect_b32 s47, s61, s47
	s_cselect_b32 s46, s60, vcc_lo
	s_cselect_b32 vcc_hi, s63, s64
	s_cselect_b32 vcc_lo, s62, s21
	s_add_i32 s11, 0, 0x14000
	v_add_u32_e32 v140, s10, v237
	v_add_u32_e32 v156, s11, v237
	ds_read_b128 v[128:131], v140
	ds_read_b128 v[132:135], v140 offset:1024
	ds_read_b128 v[136:139], v140 offset:2048
	ds_read_b128 v[140:143], v140 offset:3072
	ds_read_b128 v[144:147], v156
	ds_read_b128 v[148:151], v156 offset:1024
	ds_read_b128 v[152:155], v156 offset:2048
	ds_read_b128 v[156:159], v156 offset:3072
	v_lshl_add_u64 v[240:241], s[40:41], 0, v[186:187]
	s_add_i32 m0, s88, 0xc000
	ds_read_b128 v[190:193], v239
	ds_read_b128 v[194:197], v239 offset:1024
	ds_read_b128 v[198:201], v239 offset:2048
	ds_read_b128 v[202:205], v239 offset:3072
	ds_read_b128 v[206:209], v239 offset:4096
	ds_read_b128 v[210:213], v239 offset:5120
	ds_read_b128 v[214:217], v239 offset:6144
	ds_read_b128 v[218:221], v239 offset:7168
	global_load_lds_dwordx4 v[240:241], off
	v_lshl_add_u64 v[240:241], s[40:41], 0, v[188:189]
	s_add_i32 m0, s88, 0xe000
	s_nop 0
	global_load_lds_dwordx4 v[240:241], off
	s_cmp_eq_u32 s65, 2
	s_cselect_b32 s101, s100, 0
	s_cmp_lg_u32 s101, 0
	s_cbranch_scc1 .Lskipw_r_0
	s_waitcnt vmcnt(8)
.Lskipw_r_0:
	s_waitcnt lgkmcnt(0)
	s_barrier
	s_setprio 1
	s_waitcnt lgkmcnt(0)
	v_mfma_f32_16x16x32_bf16 v[124:127], v[128:131], v[190:193], v[124:127]
	v_mfma_f32_16x16x32_bf16 v[120:123], v[136:139], v[190:193], v[120:123]
	v_mfma_f32_16x16x32_bf16 v[108:111], v[128:131], v[198:201], v[108:111]
	v_mfma_f32_16x16x32_bf16 v[104:107], v[136:139], v[198:201], v[104:107]
	v_mfma_f32_16x16x32_bf16 v[92:95], v[128:131], v[206:209], v[92:95]
	v_mfma_f32_16x16x32_bf16 v[88:91], v[136:139], v[206:209], v[88:91]
	v_mfma_f32_16x16x32_bf16 v[76:79], v[128:131], v[214:217], v[76:79]
	v_mfma_f32_16x16x32_bf16 v[72:75], v[136:139], v[214:217], v[72:75]
	v_mfma_f32_16x16x32_bf16 v[124:127], v[132:135], v[194:197], v[124:127]
	v_mfma_f32_16x16x32_bf16 v[120:123], v[140:143], v[194:197], v[120:123]
	v_mfma_f32_16x16x32_bf16 v[108:111], v[132:135], v[202:205], v[108:111]
	v_mfma_f32_16x16x32_bf16 v[104:107], v[140:143], v[202:205], v[104:107]
	v_mfma_f32_16x16x32_bf16 v[92:95], v[132:135], v[210:213], v[92:95]
	v_mfma_f32_16x16x32_bf16 v[88:91], v[140:143], v[210:213], v[88:91]
	v_mfma_f32_16x16x32_bf16 v[76:79], v[132:135], v[218:221], v[76:79]
	v_mfma_f32_16x16x32_bf16 v[72:75], v[140:143], v[218:221], v[72:75]
	s_setprio 0
	s_setprio 1
	v_mfma_f32_16x16x32_bf16 v[116:119], v[144:147], v[190:193], v[116:119]
	v_mfma_f32_16x16x32_bf16 v[112:115], v[152:155], v[190:193], v[112:115]
	v_mfma_f32_16x16x32_bf16 v[100:103], v[144:147], v[198:201], v[100:103]
	v_mfma_f32_16x16x32_bf16 v[96:99], v[152:155], v[198:201], v[96:99]
	v_mfma_f32_16x16x32_bf16 v[84:87], v[144:147], v[206:209], v[84:87]
	v_mfma_f32_16x16x32_bf16 v[80:83], v[152:155], v[206:209], v[80:83]
	v_mfma_f32_16x16x32_bf16 v[68:71], v[144:147], v[214:217], v[68:71]
	v_mfma_f32_16x16x32_bf16 v[64:67], v[152:155], v[214:217], v[64:67]
	v_mfma_f32_16x16x32_bf16 v[116:119], v[148:151], v[194:197], v[116:119]
	v_mfma_f32_16x16x32_bf16 v[112:115], v[156:159], v[194:197], v[112:115]
	v_mfma_f32_16x16x32_bf16 v[100:103], v[148:151], v[202:205], v[100:103]
	v_mfma_f32_16x16x32_bf16 v[96:99], v[156:159], v[202:205], v[96:99]
	v_mfma_f32_16x16x32_bf16 v[84:87], v[148:151], v[210:213], v[84:87]
	v_mfma_f32_16x16x32_bf16 v[80:83], v[156:159], v[210:213], v[80:83]
	v_mfma_f32_16x16x32_bf16 v[68:71], v[148:151], v[218:221], v[68:71]
	v_mfma_f32_16x16x32_bf16 v[64:67], v[156:159], v[218:221], v[64:67]
	s_setprio 0
	s_barrier
	s_add_i32 s10, s10, s87
	v_lshl_add_u64 v[240:241], vcc, 0, v[160:161]
	s_mov_b32 m0, s10
	ds_read_b128 v[190:193], v239 offset:16384
	ds_read_b128 v[194:197], v239 offset:17408
	ds_read_b128 v[198:201], v239 offset:18432
	ds_read_b128 v[202:205], v239 offset:19456
	ds_read_b128 v[206:209], v239 offset:20480
	ds_read_b128 v[210:213], v239 offset:21504
	ds_read_b128 v[214:217], v239 offset:22528
	ds_read_b128 v[218:221], v239 offset:23552
	global_load_lds_dwordx4 v[240:241], off
	s_add_i32 m0, s10, 0x2000
	v_lshl_add_u64 v[242:243], vcc, 0, v[176:177]
	s_add_u32 vcc_lo, vcc_lo, s22
	s_addc_u32 vcc_hi, vcc_hi, 0
	s_add_i32 s10, s11, s87
	global_load_lds_dwordx4 v[242:243], off
	v_lshl_add_u64 v[244:245], vcc, 0, v[160:161]
	s_mov_b32 m0, s10
	v_lshl_add_u64 v[246:247], vcc, 0, v[176:177]
	global_load_lds_dwordx4 v[244:245], off
	s_add_i32 m0, s10, 0x2000
	v_lshl_add_u64 v[248:249], s[46:47], 0, v[180:181]
	global_load_lds_dwordx4 v[246:247], off
	s_mov_b32 m0, s88
	v_lshl_add_u64 v[250:251], s[46:47], 0, v[178:179]
	global_load_lds_dwordx4 v[248:249], off
	s_mov_b32 m0, s89
	s_nop 0
	global_load_lds_dwordx4 v[250:251], off
	s_cmp_eq_u32 s65, 2
	s_cselect_b32 s101, s100, 0
	s_cmp_lg_u32 s101, 0
	s_cbranch_scc1 .Lskipw_r_1
	s_waitcnt vmcnt(8)
; #define PG8_STAGE(bufoff, gbase, voff) do { _Pragma("unroll") for (int _i = 0; _i < 2; ++_i) \
;         __builtin_amdgcn_global_load_lds((const unsigned*)((const char*)(gbase) + (voff)[_i]), (PG8_LAS unsigned*)(lds + (bufoff) + ldsw + _i * 8192), 16, 0, 0); } while (0)
; #define PG8_LDA(dst, b, h) do { _Pragma("unroll") for (int m = 0; m < 4; ++m) _Pragma("unroll") for (int k = 0; k < 2; ++k) dst[m][k] = *(const PG8_LAS bf16x8*)(lds + PG8_SA(b, h) + aoff + m * 2048 + k * 1024); } while (0)
; #define PG8_LDB(dst, b, h) do { _Pragma("unroll") for (int n = 0; n < 2; ++n) _Pragma("unroll") for (int k = 0; k < 2; ++k) dst[n][k] = *(const PG8_LAS bf16x8*)(lds + PG8_SB(b, h) + boff + n * 2048 + k * 1024); } while (0)
; #define PG8_MMA(ai, bj, At, Bt) do { __builtin_amdgcn_s_setprio(1); _Pragma("unroll") for (int m = 0; m < 4; ++m) _Pragma("unroll") for (int n = 0; n < 2; ++n) _Pragma("unroll") for (int k = 0; k < 2; ++k) \
;         acc[ai][bj][m][n] = __builtin_amdgcn_mfma_f32_16x16x32_bf16(Bt[n][k], At[m][k], acc[ai][bj][m][n], 0, 0, 0); __builtin_amdgcn_s_setprio(0); } while (0)
; #define PG8_WAIT_V(n) asm volatile("s_waitcnt vmcnt(" #n ")" ::: "memory")
; #define PG8_WAIT_L(n) asm volatile("s_waitcnt lgkmcnt(" #n ")" ::: "memory")
; #define PG8_BAR __builtin_amdgcn_s_barrier()
; #define PG8_SCHED __builtin_amdgcn_sched_barrier(0)
; template <class Epi, class Sched, bool ALIGN_EPI = false, bool SP2 = false>
; __device__ __forceinline__ void gemm_phase(PG8_LAS unsigned char* lds, const Gemm g, const Sched& S, const Epi& E, const int tid_in) {
;     ...
;             PG8_WAIT_V(8); PG8_WAIT_L(0); PG8_BAR; PG8_MMA(1, 0, At, B0); PG8_MMA(1, 1, At, B1); PG8_BAR; PG8_SCHED;
;             PG8_LDB(B0, 1, 0); PG8_LDB(B1, 1, 1); PG8_SCHED; PG8_LDA(At, 1, 0); PG8_STAGE(PG8_SA(0, 1), a2 + hstep, voffA);
;             PG8_WAIT_V(8); PG8_WAIT_L(0); PG8_BAR; PG8_MMA(0, 0, At, B0); PG8_MMA(0, 1, At, B1); PG8_BAR; PG8_SCHED;
.Lskipw_r_1:
	s_waitcnt lgkmcnt(0)
	s_barrier
	s_setprio 1
	s_waitcnt lgkmcnt(0)
	v_mfma_f32_16x16x32_bf16 v[60:63], v[128:131], v[190:193], v[60:63]
	v_mfma_f32_16x16x32_bf16 v[56:59], v[136:139], v[190:193], v[56:59]
	v_mfma_f32_16x16x32_bf16 v[44:47], v[128:131], v[198:201], v[44:47]
	v_mfma_f32_16x16x32_bf16 v[40:43], v[136:139], v[198:201], v[40:43]
	v_mfma_f32_16x16x32_bf16 v[28:31], v[128:131], v[206:209], v[28:31]
	v_mfma_f32_16x16x32_bf16 v[24:27], v[136:139], v[206:209], v[24:27]
	v_mfma_f32_16x16x32_bf16 v[12:15], v[128:131], v[214:217], v[12:15]
	v_mfma_f32_16x16x32_bf16 v[8:11], v[136:139], v[214:217], v[8:11]
	v_mfma_f32_16x16x32_bf16 v[60:63], v[132:135], v[194:197], v[60:63]
	v_mfma_f32_16x16x32_bf16 v[56:59], v[140:143], v[194:197], v[56:59]
	v_mfma_f32_16x16x32_bf16 v[44:47], v[132:135], v[202:205], v[44:47]
	v_mfma_f32_16x16x32_bf16 v[40:43], v[140:143], v[202:205], v[40:43]
	v_mfma_f32_16x16x32_bf16 v[28:31], v[132:135], v[210:213], v[28:31]
	v_mfma_f32_16x16x32_bf16 v[24:27], v[140:143], v[210:213], v[24:27]
	v_mfma_f32_16x16x32_bf16 v[12:15], v[132:135], v[218:221], v[12:15]
	v_mfma_f32_16x16x32_bf16 v[8:11], v[140:143], v[218:221], v[8:11]
	s_setprio 0
	s_setprio 1
	v_mfma_f32_16x16x32_bf16 v[52:55], v[144:147], v[190:193], v[52:55]
	v_mfma_f32_16x16x32_bf16 v[48:51], v[152:155], v[190:193], v[48:51]
	v_mfma_f32_16x16x32_bf16 v[36:39], v[144:147], v[198:201], v[36:39]
	v_mfma_f32_16x16x32_bf16 v[32:35], v[152:155], v[198:201], v[32:35]
	v_mfma_f32_16x16x32_bf16 v[20:23], v[144:147], v[206:209], v[20:23]
	v_mfma_f32_16x16x32_bf16 v[16:19], v[152:155], v[206:209], v[16:19]
	v_mfma_f32_16x16x32_bf16 v[4:7], v[144:147], v[214:217], v[4:7]
	v_mfma_f32_16x16x32_bf16 v[0:3], v[152:155], v[214:217], v[0:3]
	v_mfma_f32_16x16x32_bf16 v[52:55], v[148:151], v[194:197], v[52:55]
	v_mfma_f32_16x16x32_bf16 v[48:51], v[156:159], v[194:197], v[48:51]
	v_mfma_f32_16x16x32_bf16 v[36:39], v[148:151], v[202:205], v[36:39]
	v_mfma_f32_16x16x32_bf16 v[32:35], v[156:159], v[202:205], v[32:35]
	v_mfma_f32_16x16x32_bf16 v[20:23], v[148:151], v[210:213], v[20:23]
	v_mfma_f32_16x16x32_bf16 v[16:19], v[156:159], v[210:213], v[16:19]
	v_mfma_f32_16x16x32_bf16 v[4:7], v[148:151], v[218:221], v[4:7]
	v_mfma_f32_16x16x32_bf16 v[0:3], v[156:159], v[218:221], v[0:3]
	s_setprio 0
	s_barrier
	s_add_i32 s10, 0, 0x18000
	s_add_i32 s11, 0, 0x1c000
	v_add_u32_e32 v140, s10, v237
	v_add_u32_e32 v156, s11, v237
	ds_read_b128 v[128:131], v140
	ds_read_b128 v[132:135], v140 offset:1024
	ds_read_b128 v[136:139], v140 offset:2048
	ds_read_b128 v[140:143], v140 offset:3072
	ds_read_b128 v[144:147], v156
	ds_read_b128 v[148:151], v156 offset:1024
	ds_read_b128 v[152:155], v156 offset:2048
	ds_read_b128 v[156:159], v156 offset:3072
	s_add_u32 s46, s46, s22
	s_addc_u32 s47, s47, 0
	s_mov_b32 m0, s90
	v_lshl_add_u64 v[232:233], s[46:47], 0, v[180:181]
	ds_read_b128 v[190:193], v239 offset:32768
	ds_read_b128 v[194:197], v239 offset:33792
	ds_read_b128 v[198:201], v239 offset:34816
	ds_read_b128 v[202:205], v239 offset:35840
	ds_read_b128 v[206:209], v239 offset:36864
	ds_read_b128 v[210:213], v239 offset:37888
	ds_read_b128 v[214:217], v239 offset:38912
	ds_read_b128 v[218:221], v239 offset:39936
	global_load_lds_dwordx4 v[232:233], off
	v_lshl_add_u64 v[232:233], s[46:47], 0, v[178:179]
	s_mov_b32 m0, s91
	s_nop 0
	global_load_lds_dwordx4 v[232:233], off
	s_waitcnt vmcnt(8)
	s_waitcnt lgkmcnt(0)
	s_barrier
	s_setprio 1
	s_waitcnt lgkmcnt(0)
	v_mfma_f32_16x16x32_bf16 v[124:127], v[128:131], v[190:193], v[124:127]
	v_mfma_f32_16x16x32_bf16 v[120:123], v[136:139], v[190:193], v[120:123]
	v_mfma_f32_16x16x32_bf16 v[108:111], v[128:131], v[198:201], v[108:111]
	v_mfma_f32_16x16x32_bf16 v[104:107], v[136:139], v[198:201], v[104:107]
	v_mfma_f32_16x16x32_bf16 v[92:95], v[128:131], v[206:209], v[92:95]
	v_mfma_f32_16x16x32_bf16 v[88:91], v[136:139], v[206:209], v[88:91]
	v_mfma_f32_16x16x32_bf16 v[76:79], v[128:131], v[214:217], v[76:79]
	v_mfma_f32_16x16x32_bf16 v[72:75], v[136:139], v[214:217], v[72:75]
	v_mfma_f32_16x16x32_bf16 v[124:127], v[132:135], v[194:197], v[124:127]
	v_mfma_f32_16x16x32_bf16 v[120:123], v[140:143], v[194:197], v[120:123]
	v_mfma_f32_16x16x32_bf16 v[108:111], v[132:135], v[202:205], v[108:111]
	v_mfma_f32_16x16x32_bf16 v[104:107], v[140:143], v[202:205], v[104:107]
	v_mfma_f32_16x16x32_bf16 v[92:95], v[132:135], v[210:213], v[92:95]
	v_mfma_f32_16x16x32_bf16 v[88:91], v[140:143], v[210:213], v[88:91]
	v_mfma_f32_16x16x32_bf16 v[76:79], v[132:135], v[218:221], v[76:79]
	v_mfma_f32_16x16x32_bf16 v[72:75], v[140:143], v[218:221], v[72:75]
	s_setprio 0
	s_setprio 1
	v_mfma_f32_16x16x32_bf16 v[116:119], v[144:147], v[190:193], v[116:119]
	v_mfma_f32_16x16x32_bf16 v[112:115], v[152:155], v[190:193], v[112:115]
	v_mfma_f32_16x16x32_bf16 v[100:103], v[144:147], v[198:201], v[100:103]
	v_mfma_f32_16x16x32_bf16 v[96:99], v[152:155], v[198:201], v[96:99]
	v_mfma_f32_16x16x32_bf16 v[84:87], v[144:147], v[206:209], v[84:87]
	v_mfma_f32_16x16x32_bf16 v[80:83], v[152:155], v[206:209], v[80:83]
	v_mfma_f32_16x16x32_bf16 v[68:71], v[144:147], v[214:217], v[68:71]
	v_mfma_f32_16x16x32_bf16 v[64:67], v[152:155], v[214:217], v[64:67]
	v_mfma_f32_16x16x32_bf16 v[116:119], v[148:151], v[194:197], v[116:119]
	v_mfma_f32_16x16x32_bf16 v[112:115], v[156:159], v[194:197], v[112:115]
	v_mfma_f32_16x16x32_bf16 v[100:103], v[148:151], v[202:205], v[100:103]
	v_mfma_f32_16x16x32_bf16 v[96:99], v[156:159], v[202:205], v[96:99]
	v_mfma_f32_16x16x32_bf16 v[84:87], v[148:151], v[210:213], v[84:87]
	v_mfma_f32_16x16x32_bf16 v[80:83], v[156:159], v[210:213], v[80:83]
	v_mfma_f32_16x16x32_bf16 v[68:71], v[148:151], v[218:221], v[68:71]
	v_mfma_f32_16x16x32_bf16 v[64:67], v[156:159], v[218:221], v[64:67]
	s_setprio 0
	s_barrier
; #define PG8_STAGE(bufoff, gbase, voff) do { _Pragma("unroll") for (int _i = 0; _i < 2; ++_i) \
;         __builtin_amdgcn_global_load_lds((const unsigned*)((const char*)(gbase) + (voff)[_i]), (PG8_LAS unsigned*)(lds + (bufoff) + ldsw + _i * 8192), 16, 0, 0); } while (0)
; #define PG8_LDA(dst, b, h) do { _Pragma("unroll") for (int m = 0; m < 4; ++m) _Pragma("unroll") for (int k = 0; k < 2; ++k) dst[m][k] = *(const PG8_LAS bf16x8*)(lds + PG8_SA(b, h) + aoff + m * 2048 + k * 1024); } while (0)
; #define PG8_MMA(ai, bj, At, Bt) do { __builtin_amdgcn_s_setprio(1); _Pragma("unroll") for (int m = 0; m < 4; ++m) _Pragma("unroll") for (int n = 0; n < 2; ++n) _Pragma("unroll") for (int k = 0; k < 2; ++k) \
;         acc[ai][bj][m][n] = __builtin_amdgcn_mfma_f32_16x16x32_bf16(Bt[n][k], At[m][k], acc[ai][bj][m][n], 0, 0, 0); __builtin_amdgcn_s_setprio(0); } while (0)
; #define PG8_WAIT_V(n) asm volatile("s_waitcnt vmcnt(" #n ")" ::: "memory")
; #define PG8_WAIT_L(n) asm volatile("s_waitcnt lgkmcnt(" #n ")" ::: "memory")
; #define PG8_BAR __builtin_amdgcn_s_barrier()
; #define PG8_SCHED __builtin_amdgcn_sched_barrier(0)
; template <class Epi, class Sched, bool ALIGN_EPI = false, bool SP2 = false>
; __device__ __forceinline__ void gemm_phase(PG8_LAS unsigned char* lds, const Gemm g, const Sched& S, const Epi& E, const int tid_in) {
;     ...
;         for (int t = 0; t < nt; t += 2) {
;             const bool last = (t == nt - 2);
;             const char* a1 = cA + (size_t)(t + 1) * kstep;
;             const char* a2 = last ? nA : cA + (size_t)(t + 2) * kstep; const char* b2 = last ? nB : cB + (size_t)(t + 2) * kstep;
;             const char* a3 = a2 + kstep; const char* b3 = b2 + kstep;
;     ...
;             PG8_LDA(At, 1, 1); PG8_STAGE(PG8_SB(1, 0), b3, voffB); PG8_STAGE(PG8_SB(1, 1), b3 + hstep, voffB); PG8_STAGE(PG8_SA(1, 0), a3, voffA);
;             PG8_WAIT_V(8); PG8_WAIT_L(0); PG8_BAR; PG8_MMA(1, 0, At, B0); PG8_MMA(1, 1, At, B1); PG8_BAR; PG8_SCHED;
	s_add_i32 s10, s10, s87
	v_lshl_add_u64 v[232:233], v[240:241], 0, s[26:27]
	s_mov_b32 m0, s10
	ds_read_b128 v[190:193], v239 offset:49152
	ds_read_b128 v[194:197], v239 offset:50176
	ds_read_b128 v[198:201], v239 offset:51200
	ds_read_b128 v[202:205], v239 offset:52224
	ds_read_b128 v[206:209], v239 offset:53248
	ds_read_b128 v[210:213], v239 offset:54272
	ds_read_b128 v[214:217], v239 offset:55296
	ds_read_b128 v[218:221], v239 offset:56320
	global_load_lds_dwordx4 v[232:233], off
	v_lshl_add_u64 v[232:233], v[242:243], 0, s[26:27]
	s_add_i32 m0, s10, 0x2000
	s_add_i32 s10, s11, s87
	global_load_lds_dwordx4 v[232:233], off
	v_lshl_add_u64 v[232:233], v[244:245], 0, s[26:27]
	s_mov_b32 m0, s10
	s_nop 0
	global_load_lds_dwordx4 v[232:233], off
	v_lshl_add_u64 v[232:233], v[246:247], 0, s[26:27]
	s_add_i32 m0, s10, 0x2000
	s_nop 0
	global_load_lds_dwordx4 v[232:233], off
	v_lshl_add_u64 v[232:233], v[248:249], 0, s[26:27]
	s_mov_b32 m0, s94
	s_nop 0
	global_load_lds_dwordx4 v[232:233], off
	v_lshl_add_u64 v[232:233], v[250:251], 0, s[26:27]
	s_mov_b32 m0, s96
	s_nop 0
	global_load_lds_dwordx4 v[232:233], off
	s_waitcnt vmcnt(8)
	s_waitcnt lgkmcnt(0)
	s_barrier
	s_setprio 1
	s_waitcnt lgkmcnt(0)
	v_mfma_f32_16x16x32_bf16 v[60:63], v[128:131], v[190:193], v[60:63]
	v_mfma_f32_16x16x32_bf16 v[56:59], v[136:139], v[190:193], v[56:59]
	v_mfma_f32_16x16x32_bf16 v[44:47], v[128:131], v[198:201], v[44:47]
	v_mfma_f32_16x16x32_bf16 v[40:43], v[136:139], v[198:201], v[40:43]
	v_mfma_f32_16x16x32_bf16 v[28:31], v[128:131], v[206:209], v[28:31]
	v_mfma_f32_16x16x32_bf16 v[24:27], v[136:139], v[206:209], v[24:27]
	v_mfma_f32_16x16x32_bf16 v[12:15], v[128:131], v[214:217], v[12:15]
	v_mfma_f32_16x16x32_bf16 v[8:11], v[136:139], v[214:217], v[8:11]
	v_mfma_f32_16x16x32_bf16 v[60:63], v[132:135], v[194:197], v[60:63]
	v_mfma_f32_16x16x32_bf16 v[56:59], v[140:143], v[194:197], v[56:59]
	v_mfma_f32_16x16x32_bf16 v[44:47], v[132:135], v[202:205], v[44:47]
	v_mfma_f32_16x16x32_bf16 v[40:43], v[140:143], v[202:205], v[40:43]
	v_mfma_f32_16x16x32_bf16 v[28:31], v[132:135], v[210:213], v[28:31]
	v_mfma_f32_16x16x32_bf16 v[24:27], v[140:143], v[210:213], v[24:27]
	v_mfma_f32_16x16x32_bf16 v[12:15], v[132:135], v[218:221], v[12:15]
	v_mfma_f32_16x16x32_bf16 v[8:11], v[140:143], v[218:221], v[8:11]
	s_setprio 0
	s_setprio 1
	v_mfma_f32_16x16x32_bf16 v[52:55], v[144:147], v[190:193], v[52:55]
	v_mfma_f32_16x16x32_bf16 v[48:51], v[152:155], v[190:193], v[48:51]
	v_mfma_f32_16x16x32_bf16 v[36:39], v[144:147], v[198:201], v[36:39]
	v_mfma_f32_16x16x32_bf16 v[32:35], v[152:155], v[198:201], v[32:35]
	v_mfma_f32_16x16x32_bf16 v[20:23], v[144:147], v[206:209], v[20:23]
	v_mfma_f32_16x16x32_bf16 v[16:19], v[152:155], v[206:209], v[16:19]
	v_mfma_f32_16x16x32_bf16 v[4:7], v[144:147], v[214:217], v[4:7]
	v_mfma_f32_16x16x32_bf16 v[0:3], v[152:155], v[214:217], v[0:3]
	v_mfma_f32_16x16x32_bf16 v[52:55], v[148:151], v[194:197], v[52:55]
	v_mfma_f32_16x16x32_bf16 v[48:51], v[156:159], v[194:197], v[48:51]
	v_mfma_f32_16x16x32_bf16 v[36:39], v[148:151], v[202:205], v[36:39]
	v_mfma_f32_16x16x32_bf16 v[32:35], v[156:159], v[202:205], v[32:35]
	v_mfma_f32_16x16x32_bf16 v[20:23], v[148:151], v[210:213], v[20:23]
	v_mfma_f32_16x16x32_bf16 v[16:19], v[156:159], v[210:213], v[16:19]
	v_mfma_f32_16x16x32_bf16 v[4:7], v[148:151], v[218:221], v[4:7]
	v_mfma_f32_16x16x32_bf16 v[0:3], v[156:159], v[218:221], v[0:3]
	s_setprio 0
	s_barrier
	s_add_u32 s40, s40, 0x100
	s_addc_u32 s41, s41, 0
	s_add_u32 s21, s21, 0x100
	s_addc_u32 s64, s64, 0
	s_cmp_ge_u32 s65, s98
	s_mov_b32 s46, s65
	s_cbranch_scc0 .LBB0_322
	s_and_b64 vcc, exec, s[48:49]
	s_cbranch_vccz .LBB0_325
	s_barrier

; #define PG8_BAR __builtin_amdgcn_s_barrier()
; template <class Epi, class Sched, bool ALIGN_EPI = false, bool SP2 = false>
; __device__ __forceinline__ void gemm_phase(PG8_LAS unsigned char* lds, const Gemm g, const Sched& S, const Epi& E, const int tid_in) {
;     ...
;         if (!has_next) break;
; #pragma unroll
;         for (int a = 0; a < 2; ++a)
; #pragma unroll
;             for (int b = 0; b < 2; ++b)
; #pragma unroll
;                 for (int m = 0; m < 4; ++m)
; #pragma unroll
;                     for (int n = 0; n < 2; ++n) acc[a][b][m][n] = (f32x4){0.f, 0.f, 0.f, 0.f};
;         cur = nxt; cA = nA; cB = nB; ++ui;
;         if constexpr (ALIGN_EPI) { if (wr == 1) PG8_BAR; }
.LBB0_385:
	v_readlane_b32 s46, v255, 2
	s_and_b64 vcc, exec, s[44:45]
	s_mov_b64 s[40:41], -1
	v_readlane_b32 s47, v255, 3
	s_mov_b32 s100, 1
	s_cbranch_vccnz .LBB0_310
	s_andn2_b64 vcc, exec, s[34:35]
	s_cbranch_vccnz .LBB0_309
	s_barrier
	s_branch .LBB0_309

; #define PG8_STAGE(bufoff, gbase, voff) do { _Pragma("unroll") for (int _i = 0; _i < 2; ++_i) \
;         __builtin_amdgcn_global_load_lds((const unsigned*)((const char*)(gbase) + (voff)[_i]), (PG8_LAS unsigned*)(lds + (bufoff) + ldsw + _i * 8192), 16, 0, 0); } while (0)
; #define PG8_LDA(dst, b, h) do { _Pragma("unroll") for (int m = 0; m < 4; ++m) _Pragma("unroll") for (int k = 0; k < 2; ++k) dst[m][k] = *(const PG8_LAS bf16x8*)(lds + PG8_SA(b, h) + aoff + m * 2048 + k * 1024); } while (0)
; #define PG8_LDB(dst, b, h) do { _Pragma("unroll") for (int n = 0; n < 2; ++n) _Pragma("unroll") for (int k = 0; k < 2; ++k) dst[n][k] = *(const PG8_LAS bf16x8*)(lds + PG8_SB(b, h) + boff + n * 2048 + k * 1024); } while (0)
; #define PG8_MMA(ai, bj, At, Bt) do { __builtin_amdgcn_s_setprio(1); _Pragma("unroll") for (int m = 0; m < 4; ++m) _Pragma("unroll") for (int n = 0; n < 2; ++n) _Pragma("unroll") for (int k = 0; k < 2; ++k) \
;         acc[ai][bj][m][n] = __builtin_amdgcn_mfma_f32_16x16x32_bf16(Bt[n][k], At[m][k], acc[ai][bj][m][n], 0, 0, 0); __builtin_amdgcn_s_setprio(0); } while (0)
; #define PG8_WAIT_V(n) asm volatile("s_waitcnt vmcnt(" #n ")" ::: "memory")
; #define PG8_BAR __builtin_amdgcn_s_barrier()
; template <class Epi, class Sched, bool ALIGN_EPI = false, bool SP2 = false>
; __device__ __forceinline__ void gemm_phase(PG8_LAS unsigned char* lds, const Gemm g, const Sched& S, const Epi& E, const int tid_in) {
;     ...
;         for (int t = 0; t < nt; t += 2) {
;             const bool last = (t == nt - 2);
;             const char* a1 = cA + (size_t)(t + 1) * kstep;
;             const char* a2 = last ? nA : cA + (size_t)(t + 2) * kstep; const char* b2 = last ? nB : cB + (size_t)(t + 2) * kstep;
;             const char* a3 = a2 + kstep; const char* b3 = b2 + kstep;
;             if (last && has_next) S.a_ready(nxt);
;             if constexpr (SP2) {
;             PG8_LDB(B0, 0, 0); PG8_LDB(B1, 0, 1); PG8_SCHED; PG8_LDA(At, 0, 0); PG8_STAGE(PG8_SA(1, 1), a1 + hstep, voffA);
;             PG8_WAIT_V(8); PG8_WAIT_L(0); PG8_BAR; PG8_MMA(0, 0, At, B0); PG8_MMA(0, 1, At, B1); PG8_BAR; PG8_SCHED;
;             PG8_LDA(At, 0, 1); PG8_STAGE(PG8_SB(0, 0), b2, voffB); PG8_STAGE(PG8_SB(0, 1), b2 + hstep, voffB); PG8_STAGE(PG8_SA(0, 0), a2, voffA);
;             PG8_WAIT_V(8); PG8_WAIT_L(0); PG8_BAR; PG8_MMA(1, 0, At, B0); PG8_MMA(1, 1, At, B1); PG8_BAR; PG8_SCHED;
.LBB0_400:
	s_add_u32 s52, s40, 0xfffc0080
	s_addc_u32 s53, s41, -1
	s_add_i32 s87, 0, 0x10000
	s_cmp_eq_u32 s47, 12
	s_cselect_b32 s55, s9, s53
	s_cselect_b32 s54, s16, s52
	s_cselect_b32 s53, s17, s45
	s_cselect_b32 s52, s20, s21
	s_add_i32 s90, 0, 0x14000
	v_add_u32_e32 v60, s87, v180
	v_add_u32_e32 v158, s90, v180
	ds_read_b128 v[48:51], v60
	ds_read_b128 v[52:55], v60 offset:1024
	ds_read_b128 v[56:59], v60 offset:2048
	ds_read_b128 v[60:63], v60 offset:3072
	ds_read_b128 v[154:157], v158
	ds_read_b128 v[176:179], v158 offset:1024
	ds_read_b128 v[184:187], v158 offset:2048
	ds_read_b128 v[188:191], v158 offset:3072
	v_lshl_add_u64 v[158:159], s[40:41], 0, v[150:151]
	s_add_i32 m0, s58, 0xc000
	ds_read_b128 v[192:195], v182
	ds_read_b128 v[196:199], v182 offset:1024
	ds_read_b128 v[200:203], v182 offset:2048
	ds_read_b128 v[204:207], v182 offset:3072
	ds_read_b128 v[208:211], v182 offset:4096
	ds_read_b128 v[212:215], v182 offset:5120
	ds_read_b128 v[216:219], v182 offset:6144
	ds_read_b128 v[238:241], v182 offset:7168
	global_load_lds_dwordx4 v[158:159], off
	v_lshl_add_u64 v[158:159], s[40:41], 0, v[152:153]
	s_add_i32 m0, s58, 0xe000
	s_nop 0
	global_load_lds_dwordx4 v[158:159], off
	s_cmp_eq_u32 s47, 0
	s_cselect_b32 s101, s100, 0
	s_cmp_lg_u32 s101, 0
	s_cbranch_scc1 .Lskipw_s_0
	s_waitcnt vmcnt(8)
.Lskipw_s_0:
	s_waitcnt lgkmcnt(0)
	s_barrier
	s_setprio 1
	s_waitcnt lgkmcnt(0)
	v_mfma_f32_16x16x32_bf16 v[140:143], v[48:51], v[192:195], v[140:143]
	v_mfma_f32_16x16x32_bf16 v[136:139], v[56:59], v[192:195], v[136:139]
	v_mfma_f32_16x16x32_bf16 v[124:127], v[48:51], v[200:203], v[124:127]
	v_mfma_f32_16x16x32_bf16 v[120:123], v[56:59], v[200:203], v[120:123]
	v_mfma_f32_16x16x32_bf16 v[108:111], v[48:51], v[208:211], v[108:111]
	v_mfma_f32_16x16x32_bf16 v[104:107], v[56:59], v[208:211], v[104:107]
	v_mfma_f32_16x16x32_bf16 v[92:95], v[48:51], v[216:219], v[92:95]
	v_mfma_f32_16x16x32_bf16 v[88:91], v[56:59], v[216:219], v[88:91]
	v_mfma_f32_16x16x32_bf16 v[140:143], v[52:55], v[196:199], v[140:143]
	v_mfma_f32_16x16x32_bf16 v[136:139], v[60:63], v[196:199], v[136:139]
	v_mfma_f32_16x16x32_bf16 v[124:127], v[52:55], v[204:207], v[124:127]
	v_mfma_f32_16x16x32_bf16 v[120:123], v[60:63], v[204:207], v[120:123]
	v_mfma_f32_16x16x32_bf16 v[108:111], v[52:55], v[212:215], v[108:111]
	v_mfma_f32_16x16x32_bf16 v[104:107], v[60:63], v[212:215], v[104:107]
	v_mfma_f32_16x16x32_bf16 v[92:95], v[52:55], v[238:241], v[92:95]
	v_mfma_f32_16x16x32_bf16 v[88:91], v[60:63], v[238:241], v[88:91]
	s_setprio 0
	s_setprio 1
	v_mfma_f32_16x16x32_bf16 v[132:135], v[154:157], v[192:195], v[132:135]
	v_mfma_f32_16x16x32_bf16 v[128:131], v[184:187], v[192:195], v[128:131]
	v_mfma_f32_16x16x32_bf16 v[116:119], v[154:157], v[200:203], v[116:119]
	v_mfma_f32_16x16x32_bf16 v[112:115], v[184:187], v[200:203], v[112:115]
	v_mfma_f32_16x16x32_bf16 v[100:103], v[154:157], v[208:211], v[100:103]
	v_mfma_f32_16x16x32_bf16 v[96:99], v[184:187], v[208:211], v[96:99]
	v_mfma_f32_16x16x32_bf16 v[84:87], v[154:157], v[216:219], v[84:87]
	v_mfma_f32_16x16x32_bf16 v[80:83], v[184:187], v[216:219], v[80:83]
	v_mfma_f32_16x16x32_bf16 v[132:135], v[176:179], v[196:199], v[132:135]
	v_mfma_f32_16x16x32_bf16 v[128:131], v[188:191], v[196:199], v[128:131]
	v_mfma_f32_16x16x32_bf16 v[116:119], v[176:179], v[204:207], v[116:119]
	v_mfma_f32_16x16x32_bf16 v[112:115], v[188:191], v[204:207], v[112:115]
	v_mfma_f32_16x16x32_bf16 v[100:103], v[176:179], v[212:215], v[100:103]
	v_mfma_f32_16x16x32_bf16 v[96:99], v[188:191], v[212:215], v[96:99]
	v_mfma_f32_16x16x32_bf16 v[84:87], v[176:179], v[238:241], v[84:87]
	v_mfma_f32_16x16x32_bf16 v[80:83], v[188:191], v[238:241], v[80:83]
	s_setprio 0
	s_barrier
	s_add_i32 s87, s87, s57
	v_lshl_add_u64 v[158:159], s[52:53], 0, v[160:161]
	s_mov_b32 m0, s87
	ds_read_b128 v[192:195], v182 offset:16384
	ds_read_b128 v[196:199], v182 offset:17408
	ds_read_b128 v[200:203], v182 offset:18432
	ds_read_b128 v[204:207], v182 offset:19456
	ds_read_b128 v[208:211], v182 offset:20480
	ds_read_b128 v[212:215], v182 offset:21504
	ds_read_b128 v[216:219], v182 offset:22528
	ds_read_b128 v[238:241], v182 offset:23552
	global_load_lds_dwordx4 v[158:159], off
	s_add_i32 m0, s87, 0x2000
	s_add_u32 s88, s52, 0x40000
	v_lshl_add_u64 v[220:221], s[52:53], 0, v[144:145]
	s_addc_u32 s89, s53, 0
	s_add_i32 s87, s90, s57
	global_load_lds_dwordx4 v[220:221], off
	v_lshl_add_u64 v[242:243], s[88:89], 0, v[160:161]
	s_mov_b32 m0, s87
	v_lshl_add_u64 v[244:245], s[54:55], 0, v[146:147]
	global_load_lds_dwordx4 v[242:243], off
	v_lshl_add_u64 v[242:243], s[88:89], 0, v[144:145]
	s_add_i32 m0, s87, 0x2000
	s_nop 0
	global_load_lds_dwordx4 v[242:243], off
	v_lshl_add_u64 v[242:243], s[54:55], 0, v[148:149]
	s_mov_b32 m0, s58
	s_nop 0
	global_load_lds_dwordx4 v[242:243], off
	s_mov_b32 m0, s59
	s_nop 0
	global_load_lds_dwordx4 v[244:245], off
	s_cmp_eq_u32 s47, 0
	s_cselect_b32 s101, s100, 0
	s_cmp_lg_u32 s101, 0
	s_cbranch_scc1 .Lskipw_s_1
	s_waitcnt vmcnt(8)
; #define PG8_STAGE(bufoff, gbase, voff) do { _Pragma("unroll") for (int _i = 0; _i < 2; ++_i) \
;         __builtin_amdgcn_global_load_lds((const unsigned*)((const char*)(gbase) + (voff)[_i]), (PG8_LAS unsigned*)(lds + (bufoff) + ldsw + _i * 8192), 16, 0, 0); } while (0)
; #define PG8_LDA(dst, b, h) do { _Pragma("unroll") for (int m = 0; m < 4; ++m) _Pragma("unroll") for (int k = 0; k < 2; ++k) dst[m][k] = *(const PG8_LAS bf16x8*)(lds + PG8_SA(b, h) + aoff + m * 2048 + k * 1024); } while (0)
; #define PG8_LDB(dst, b, h) do { _Pragma("unroll") for (int n = 0; n < 2; ++n) _Pragma("unroll") for (int k = 0; k < 2; ++k) dst[n][k] = *(const PG8_LAS bf16x8*)(lds + PG8_SB(b, h) + boff + n * 2048 + k * 1024); } while (0)
; #define PG8_MMA(ai, bj, At, Bt) do { __builtin_amdgcn_s_setprio(1); _Pragma("unroll") for (int m = 0; m < 4; ++m) _Pragma("unroll") for (int n = 0; n < 2; ++n) _Pragma("unroll") for (int k = 0; k < 2; ++k) \
;         acc[ai][bj][m][n] = __builtin_amdgcn_mfma_f32_16x16x32_bf16(Bt[n][k], At[m][k], acc[ai][bj][m][n], 0, 0, 0); __builtin_amdgcn_s_setprio(0); } while (0)
; #define PG8_WAIT_V(n) asm volatile("s_waitcnt vmcnt(" #n ")" ::: "memory")
; #define PG8_WAIT_L(n) asm volatile("s_waitcnt lgkmcnt(" #n ")" ::: "memory")
; #define PG8_BAR __builtin_amdgcn_s_barrier()
; #define PG8_SCHED __builtin_amdgcn_sched_barrier(0)
; template <class Epi, class Sched, bool ALIGN_EPI = false, bool SP2 = false>
; __device__ __forceinline__ void gemm_phase(PG8_LAS unsigned char* lds, const Gemm g, const Sched& S, const Epi& E, const int tid_in) {
;     ...
;             PG8_WAIT_V(8); PG8_WAIT_L(0); PG8_BAR; PG8_MMA(1, 0, At, B0); PG8_MMA(1, 1, At, B1); PG8_BAR; PG8_SCHED;
;             PG8_LDB(B0, 1, 0); PG8_LDB(B1, 1, 1); PG8_SCHED; PG8_LDA(At, 1, 0); PG8_STAGE(PG8_SA(0, 1), a2 + hstep, voffA);
;             PG8_WAIT_V(8); PG8_WAIT_L(0); PG8_BAR; PG8_MMA(0, 0, At, B0); PG8_MMA(0, 1, At, B1); PG8_BAR; PG8_SCHED;
.Lskipw_s_1:
	s_waitcnt lgkmcnt(0)
	s_barrier
	s_setprio 1
	s_waitcnt lgkmcnt(0)
	v_mfma_f32_16x16x32_bf16 v[76:79], v[48:51], v[192:195], v[76:79]
	v_mfma_f32_16x16x32_bf16 v[72:75], v[56:59], v[192:195], v[72:75]
	v_mfma_f32_16x16x32_bf16 v[44:47], v[48:51], v[200:203], v[44:47]
	v_mfma_f32_16x16x32_bf16 v[40:43], v[56:59], v[200:203], v[40:43]
	v_mfma_f32_16x16x32_bf16 v[28:31], v[48:51], v[208:211], v[28:31]
	v_mfma_f32_16x16x32_bf16 v[24:27], v[56:59], v[208:211], v[24:27]
	v_mfma_f32_16x16x32_bf16 v[12:15], v[48:51], v[216:219], v[12:15]
	v_mfma_f32_16x16x32_bf16 v[8:11], v[56:59], v[216:219], v[8:11]
	v_mfma_f32_16x16x32_bf16 v[76:79], v[52:55], v[196:199], v[76:79]
	v_mfma_f32_16x16x32_bf16 v[72:75], v[60:63], v[196:199], v[72:75]
	v_mfma_f32_16x16x32_bf16 v[44:47], v[52:55], v[204:207], v[44:47]
	v_mfma_f32_16x16x32_bf16 v[40:43], v[60:63], v[204:207], v[40:43]
	v_mfma_f32_16x16x32_bf16 v[28:31], v[52:55], v[212:215], v[28:31]
	v_mfma_f32_16x16x32_bf16 v[24:27], v[60:63], v[212:215], v[24:27]
	v_mfma_f32_16x16x32_bf16 v[12:15], v[52:55], v[238:241], v[12:15]
	v_mfma_f32_16x16x32_bf16 v[8:11], v[60:63], v[238:241], v[8:11]
	s_setprio 0
	s_setprio 1
	v_mfma_f32_16x16x32_bf16 v[36:39], v[154:157], v[200:203], v[36:39]
	v_mfma_f32_16x16x32_bf16 v[32:35], v[184:187], v[200:203], v[32:35]
	v_mfma_f32_16x16x32_bf16 v[20:23], v[154:157], v[208:211], v[20:23]
	v_mfma_f32_16x16x32_bf16 v[16:19], v[184:187], v[208:211], v[16:19]
	v_mfma_f32_16x16x32_bf16 v[4:7], v[154:157], v[216:219], v[4:7]
	v_mfma_f32_16x16x32_bf16 v[0:3], v[184:187], v[216:219], v[0:3]
	v_mfma_f32_16x16x32_bf16 v[48:51], v[154:157], v[192:195], v[68:71]
	v_mfma_f32_16x16x32_bf16 v[52:55], v[184:187], v[192:195], v[64:67]
	v_mfma_f32_16x16x32_bf16 v[36:39], v[176:179], v[204:207], v[36:39]
	v_mfma_f32_16x16x32_bf16 v[32:35], v[188:191], v[204:207], v[32:35]
	v_mfma_f32_16x16x32_bf16 v[20:23], v[176:179], v[212:215], v[20:23]
	v_mfma_f32_16x16x32_bf16 v[16:19], v[188:191], v[212:215], v[16:19]
	v_mfma_f32_16x16x32_bf16 v[4:7], v[176:179], v[238:241], v[4:7]
	v_mfma_f32_16x16x32_bf16 v[0:3], v[188:191], v[238:241], v[0:3]
	v_mfma_f32_16x16x32_bf16 v[48:51], v[176:179], v[196:199], v[48:51]
	v_mfma_f32_16x16x32_bf16 v[52:55], v[188:191], v[196:199], v[52:55]
	s_setprio 0
	s_barrier
	s_add_i32 s87, 0, 0x18000
	s_add_i32 s88, 0, 0x1c000
	v_add_u32_e32 v68, s87, v180
	v_add_u32_e32 v188, s88, v180
	ds_read_b128 v[56:59], v68
	ds_read_b128 v[60:63], v68 offset:1024
	ds_read_b128 v[64:67], v68 offset:2048
	ds_read_b128 v[68:71], v68 offset:3072
	ds_read_b128 v[154:157], v188
	ds_read_b128 v[176:179], v188 offset:1024
	ds_read_b128 v[184:187], v188 offset:2048
	ds_read_b128 v[188:191], v188 offset:3072
	s_add_u32 s54, s54, 0x40000
	s_addc_u32 s55, s55, 0
	s_mov_b32 m0, s60
	v_lshl_add_u64 v[246:247], s[54:55], 0, v[148:149]
	ds_read_b128 v[192:195], v182 offset:32768
	ds_read_b128 v[196:199], v182 offset:33792
	ds_read_b128 v[200:203], v182 offset:34816
	ds_read_b128 v[204:207], v182 offset:35840
	ds_read_b128 v[208:211], v182 offset:36864
	ds_read_b128 v[212:215], v182 offset:37888
	ds_read_b128 v[216:219], v182 offset:38912
	ds_read_b128 v[238:241], v182 offset:39936
	global_load_lds_dwordx4 v[246:247], off
	v_lshl_add_u64 v[246:247], s[54:55], 0, v[146:147]
	s_mov_b32 m0, s61
	s_nop 0
	global_load_lds_dwordx4 v[246:247], off
	s_waitcnt vmcnt(8)
	s_waitcnt lgkmcnt(0)
	s_barrier
	s_setprio 1
	s_waitcnt lgkmcnt(0)
	v_mfma_f32_16x16x32_bf16 v[140:143], v[56:59], v[192:195], v[140:143]
	v_mfma_f32_16x16x32_bf16 v[136:139], v[64:67], v[192:195], v[136:139]
	v_mfma_f32_16x16x32_bf16 v[124:127], v[56:59], v[200:203], v[124:127]
	v_mfma_f32_16x16x32_bf16 v[120:123], v[64:67], v[200:203], v[120:123]
	v_mfma_f32_16x16x32_bf16 v[108:111], v[56:59], v[208:211], v[108:111]
	v_mfma_f32_16x16x32_bf16 v[104:107], v[64:67], v[208:211], v[104:107]
	v_mfma_f32_16x16x32_bf16 v[92:95], v[56:59], v[216:219], v[92:95]
	v_mfma_f32_16x16x32_bf16 v[88:91], v[64:67], v[216:219], v[88:91]
	v_mfma_f32_16x16x32_bf16 v[140:143], v[60:63], v[196:199], v[140:143]
	v_mfma_f32_16x16x32_bf16 v[136:139], v[68:71], v[196:199], v[136:139]
	v_mfma_f32_16x16x32_bf16 v[124:127], v[60:63], v[204:207], v[124:127]
	v_mfma_f32_16x16x32_bf16 v[120:123], v[68:71], v[204:207], v[120:123]
	v_mfma_f32_16x16x32_bf16 v[108:111], v[60:63], v[212:215], v[108:111]
	v_mfma_f32_16x16x32_bf16 v[104:107], v[68:71], v[212:215], v[104:107]
	v_mfma_f32_16x16x32_bf16 v[92:95], v[60:63], v[238:241], v[92:95]
	v_mfma_f32_16x16x32_bf16 v[88:91], v[68:71], v[238:241], v[88:91]
	s_setprio 0
	s_setprio 1
	v_mfma_f32_16x16x32_bf16 v[132:135], v[154:157], v[192:195], v[132:135]
	v_mfma_f32_16x16x32_bf16 v[128:131], v[184:187], v[192:195], v[128:131]
	v_mfma_f32_16x16x32_bf16 v[116:119], v[154:157], v[200:203], v[116:119]
	v_mfma_f32_16x16x32_bf16 v[112:115], v[184:187], v[200:203], v[112:115]
	v_mfma_f32_16x16x32_bf16 v[100:103], v[154:157], v[208:211], v[100:103]
	v_mfma_f32_16x16x32_bf16 v[96:99], v[184:187], v[208:211], v[96:99]
	v_mfma_f32_16x16x32_bf16 v[84:87], v[154:157], v[216:219], v[84:87]
	v_mfma_f32_16x16x32_bf16 v[80:83], v[184:187], v[216:219], v[80:83]
	v_mfma_f32_16x16x32_bf16 v[132:135], v[176:179], v[196:199], v[132:135]
	v_mfma_f32_16x16x32_bf16 v[128:131], v[188:191], v[196:199], v[128:131]
	v_mfma_f32_16x16x32_bf16 v[116:119], v[176:179], v[204:207], v[116:119]
	v_mfma_f32_16x16x32_bf16 v[112:115], v[188:191], v[204:207], v[112:115]
	v_mfma_f32_16x16x32_bf16 v[100:103], v[176:179], v[212:215], v[100:103]
	v_mfma_f32_16x16x32_bf16 v[96:99], v[188:191], v[212:215], v[96:99]
	v_mfma_f32_16x16x32_bf16 v[84:87], v[176:179], v[238:241], v[84:87]
	v_mfma_f32_16x16x32_bf16 v[80:83], v[188:191], v[238:241], v[80:83]
	s_setprio 0
	s_barrier
; #define PG8_STAGE(bufoff, gbase, voff) do { _Pragma("unroll") for (int _i = 0; _i < 2; ++_i) \
;         __builtin_amdgcn_global_load_lds((const unsigned*)((const char*)(gbase) + (voff)[_i]), (PG8_LAS unsigned*)(lds + (bufoff) + ldsw + _i * 8192), 16, 0, 0); } while (0)
; #define PG8_LDA(dst, b, h) do { _Pragma("unroll") for (int m = 0; m < 4; ++m) _Pragma("unroll") for (int k = 0; k < 2; ++k) dst[m][k] = *(const PG8_LAS bf16x8*)(lds + PG8_SA(b, h) + aoff + m * 2048 + k * 1024); } while (0)
; #define PG8_MMA(ai, bj, At, Bt) do { __builtin_amdgcn_s_setprio(1); _Pragma("unroll") for (int m = 0; m < 4; ++m) _Pragma("unroll") for (int n = 0; n < 2; ++n) _Pragma("unroll") for (int k = 0; k < 2; ++k) \
;         acc[ai][bj][m][n] = __builtin_amdgcn_mfma_f32_16x16x32_bf16(Bt[n][k], At[m][k], acc[ai][bj][m][n], 0, 0, 0); __builtin_amdgcn_s_setprio(0); } while (0)
; #define PG8_WAIT_V(n) asm volatile("s_waitcnt vmcnt(" #n ")" ::: "memory")
; #define PG8_WAIT_L(n) asm volatile("s_waitcnt lgkmcnt(" #n ")" ::: "memory")
; template <class Epi, class Sched, bool ALIGN_EPI = false, bool SP2 = false>
; __device__ __forceinline__ void gemm_phase(PG8_LAS unsigned char* lds, const Gemm g, const Sched& S, const Epi& E, const int tid_in) {
;     ...
;             PG8_LDA(At, 1, 1); PG8_STAGE(PG8_SB(1, 0), b3, voffB); PG8_STAGE(PG8_SB(1, 1), b3 + hstep, voffB); PG8_STAGE(PG8_SA(1, 0), a3, voffA);
;             PG8_WAIT_V(8); PG8_WAIT_L(0); PG8_BAR; PG8_MMA(1, 0, At, B0); PG8_MMA(1, 1, At, B1); PG8_BAR; PG8_SCHED;
;     __device__ __forceinline__ void operator()(const f32x4 (&acc)[2][2][4][2], const Unit& u, int wr, int wc, int fr, int fq) const {
;         const int r00 = u.pm * BM;
;         const int b = r00 < 32768 ? (r00 >> 11) : 16 + ((r00 - 32768) >> 12);
;         const int row0 = r00 + wr * 64 + fr; const int col0 = u.pn * 128 + wc * 32 + 8 * fq;
;         const float* sp = shw + (size_t)b * 5632 + u.pn * BM + wc * 32 + 8 * fq;
;         const f32x4 sg0 = *(const f32x4*)(sp), sg1 = *(const f32x4*)(sp + 4), su0 = *(const f32x4*)(sp + HALF), su1 = *(const f32x4*)(sp + HALF + 4);
; #pragma unroll
;         for (int ai = 0; ai < 2; ++ai)
; #pragma unroll
;             for (int m = 0; m < 4; ++m) {
;                 const int row = row0 + ai * HALF + m * 16;
;                 const float rs = __builtin_amdgcn_rsqf(ssq[row] * (1.0f / 1024.0f) + 1e-6f);
	s_add_i32 s54, s87, s57
	v_lshl_add_u64 v[158:159], v[158:159], 0, s[26:27]
	s_mov_b32 m0, s54
	ds_read_b128 v[192:195], v182 offset:49152
	ds_read_b128 v[196:199], v182 offset:50176
	ds_read_b128 v[200:203], v182 offset:51200
	ds_read_b128 v[204:207], v182 offset:52224
	ds_read_b128 v[208:211], v182 offset:53248
	ds_read_b128 v[212:215], v182 offset:54272
	ds_read_b128 v[216:219], v182 offset:55296
	ds_read_b128 v[238:241], v182 offset:56320
	global_load_lds_dwordx4 v[158:159], off
	s_add_i32 m0, s54, 0x2000
	s_add_u32 s52, s52, 0x40080
	v_lshl_add_u64 v[158:159], v[220:221], 0, s[26:27]
	s_addc_u32 s53, s53, 0
	s_add_i32 s54, s88, s57
	global_load_lds_dwordx4 v[158:159], off
	v_lshl_add_u64 v[158:159], s[52:53], 0, v[160:161]
	s_mov_b32 m0, s54
	s_nop 0
	global_load_lds_dwordx4 v[158:159], off
	v_lshl_add_u64 v[158:159], s[52:53], 0, v[144:145]
	s_add_i32 m0, s54, 0x2000
	s_nop 0
	global_load_lds_dwordx4 v[158:159], off
	v_lshl_add_u64 v[158:159], v[242:243], 0, s[26:27]
	s_mov_b32 m0, s64
	s_nop 0
	global_load_lds_dwordx4 v[158:159], off
	v_lshl_add_u64 v[158:159], v[244:245], 0, s[26:27]
	s_mov_b32 m0, s65
	s_nop 0
	global_load_lds_dwordx4 v[158:159], off
	s_waitcnt vmcnt(8)
	s_waitcnt lgkmcnt(0)
	s_barrier
	s_setprio 1
	s_waitcnt lgkmcnt(0)
	v_mfma_f32_16x16x32_bf16 v[76:79], v[56:59], v[192:195], v[76:79]
	v_mfma_f32_16x16x32_bf16 v[72:75], v[64:67], v[192:195], v[72:75]
	v_mfma_f32_16x16x32_bf16 v[44:47], v[56:59], v[200:203], v[44:47]
	v_mfma_f32_16x16x32_bf16 v[40:43], v[64:67], v[200:203], v[40:43]
	v_mfma_f32_16x16x32_bf16 v[28:31], v[56:59], v[208:211], v[28:31]
	v_mfma_f32_16x16x32_bf16 v[24:27], v[64:67], v[208:211], v[24:27]
	v_mfma_f32_16x16x32_bf16 v[12:15], v[56:59], v[216:219], v[12:15]
	v_mfma_f32_16x16x32_bf16 v[8:11], v[64:67], v[216:219], v[8:11]
	v_mfma_f32_16x16x32_bf16 v[76:79], v[60:63], v[196:199], v[76:79]
	v_mfma_f32_16x16x32_bf16 v[72:75], v[68:71], v[196:199], v[72:75]
	v_mfma_f32_16x16x32_bf16 v[44:47], v[60:63], v[204:207], v[44:47]
	v_mfma_f32_16x16x32_bf16 v[40:43], v[68:71], v[204:207], v[40:43]
	v_mfma_f32_16x16x32_bf16 v[28:31], v[60:63], v[212:215], v[28:31]
	v_mfma_f32_16x16x32_bf16 v[24:27], v[68:71], v[212:215], v[24:27]
	v_mfma_f32_16x16x32_bf16 v[12:15], v[60:63], v[238:241], v[12:15]
	v_mfma_f32_16x16x32_bf16 v[8:11], v[68:71], v[238:241], v[8:11]
	s_setprio 0
	s_setprio 1
	v_mfma_f32_16x16x32_bf16 v[48:51], v[154:157], v[192:195], v[48:51]
	v_mfma_f32_16x16x32_bf16 v[68:71], v[176:179], v[196:199], v[48:51]
	v_mfma_f32_16x16x32_bf16 v[48:51], v[184:187], v[192:195], v[52:55]
	v_mfma_f32_16x16x32_bf16 v[36:39], v[154:157], v[200:203], v[36:39]
	v_mfma_f32_16x16x32_bf16 v[32:35], v[184:187], v[200:203], v[32:35]
	v_mfma_f32_16x16x32_bf16 v[20:23], v[154:157], v[208:211], v[20:23]
	v_mfma_f32_16x16x32_bf16 v[16:19], v[184:187], v[208:211], v[16:19]
	v_mfma_f32_16x16x32_bf16 v[4:7], v[154:157], v[216:219], v[4:7]
	v_mfma_f32_16x16x32_bf16 v[0:3], v[184:187], v[216:219], v[0:3]
	v_mfma_f32_16x16x32_bf16 v[64:67], v[188:191], v[196:199], v[48:51]
	v_mfma_f32_16x16x32_bf16 v[36:39], v[176:179], v[204:207], v[36:39]
	v_mfma_f32_16x16x32_bf16 v[32:35], v[188:191], v[204:207], v[32:35]
	v_mfma_f32_16x16x32_bf16 v[20:23], v[176:179], v[212:215], v[20:23]
	v_mfma_f32_16x16x32_bf16 v[16:19], v[188:191], v[212:215], v[16:19]
	v_mfma_f32_16x16x32_bf16 v[4:7], v[176:179], v[238:241], v[4:7]
	v_mfma_f32_16x16x32_bf16 v[0:3], v[188:191], v[238:241], v[0:3]
	s_setprio 0
	s_barrier
	s_add_i32 s47, s47, 2
	s_add_u32 s40, s40, 0x100
	s_addc_u32 s41, s41, 0
	s_add_u32 s21, s21, 0x100
	s_addc_u32 s45, s45, 0
	s_cmp_gt_u32 s47, 13
	s_cbranch_scc0 .LBB0_400
	s_and_b64 vcc, exec, s[36:37]
	s_cbranch_vccz .LBB0_403
	s_barrier
.LBB0_403:
	s_lshl_b32 s9, s1, 8
	s_add_i32 s17, s9, 0xffff8000
	s_lshr_b32 s17, s17, 12
	s_ashr_i32 s16, s1, 3
	s_add_i32 s17, s17, 16
	s_cmpk_lt_i32 s1, 0x80
	s_cselect_b32 s1, s16, s17
	v_add_u32_e32 v154, s9, v175
	s_mul_hi_i32 s9, s1, 0x5800
	s_mulk_i32 s1, 0x5800
	s_add_u32 s16, s22, s1
	v_lshl_or_b32 v176, s0, 7, v181
	s_addc_u32 s9, s63, s9
	s_lshl_b32 s0, s0, 8
	s_ashr_i32 s1, s0, 31
	s_lshl_b64 s[0:1], s[0:1], 2
	s_add_u32 s0, s16, s0
	s_addc_u32 s1, s9, s1
	s_add_u32 s0, s0, s86
	v_ashrrev_i32_e32 v155, 31, v154
	s_addc_u32 s1, s1, 0
	v_lshl_add_u64 v[156:157], v[154:155], 2, s[28:29]
	global_load_dwordx4 v[52:55], v183, s[0:1] offset:16
	global_load_dwordx4 v[60:63], v183, s[0:1]
	global_load_dwordx4 v[48:51], v183, s[0:1] offset:528
	global_load_dwordx4 v[56:59], v183, s[0:1] offset:512
	global_load_dword v155, v[156:157], off
	global_load_dword v192, v[156:157], off offset:64
	global_load_dword v193, v[156:157], off offset:128
	global_load_dword v194, v[156:157], off offset:192
	global_load_dword v195, v[156:157], off offset:512
	global_load_dword v196, v[156:157], off offset:576
	global_load_dword v197, v[156:157], off offset:640
	global_load_dword v198, v[156:157], off offset:704
	v_ashrrev_i32_e32 v177, 31, v176
	v_mov_b64_e32 v[158:159], s[12:13]
	v_mad_i64_i32 v[178:179], s[0:1], v154, s99, v[158:159]
	v_lshlrev_b64 v[176:177], 1, v[176:177]
	v_lshl_add_u64 v[178:179], v[178:179], 0, v[176:177]
	s_mov_b64 s[40:41], -1
	s_andn2_b64 vcc, exec, s[42:43]
	s_waitcnt vmcnt(0)
; __device__ __forceinline__ unsigned cvt_pk_bf16(float lo, float hi) { unsigned r; asm volatile("v_cvt_pk_bf16_f32 %0, %1, %2" : "=v"(r) : "v"(lo), "v"(hi)); return r; }
; __device__ __forceinline__ float silu_f(float g) { return g * __builtin_amdgcn_rcpf(1.0f + __expf(-g)); }
;     __device__ __forceinline__ void operator()(const f32x4 (&acc)[2][2][4][2], const Unit& u, int wr, int wc, int fr, int fq) const {
;     ...
;             for (int m = 0; m < 4; ++m) {
;                 const int row = row0 + ai * HALF + m * 16;
;                 const float rs = __builtin_amdgcn_rsqf(ssq[row] * (1.0f / 1024.0f) + 1e-6f);
;                 bf16_t* rowp = O + (size_t)row * 2816 + col0;
;                 const f32x4 g0 = acc[ai][0][m][0] * rs + sg0, g1 = acc[ai][0][m][1] * rs + sg1, u0 = acc[ai][1][m][0] * rs + su0, u1 = acc[ai][1][m][1] * rs + su1;
;                 u32x4 w;
;                 w.x = cvt_pk_bf16(silu_f(g0[0]) * u0[0], silu_f(g0[1]) * u0[1]);
;                 w.y = cvt_pk_bf16(silu_f(g0[2]) * u0[2], silu_f(g0[3]) * u0[3]);
;                 w.z = cvt_pk_bf16(silu_f(g1[0]) * u1[0], silu_f(g1[1]) * u1[1]);
;                 w.w = cvt_pk_bf16(silu_f(g1[2]) * u1[2], silu_f(g1[3]) * u1[3]);
;                 *(u32x4*)rowp = w;
	v_mov_b32_e32 v216, 0xbfb8aa3b
	v_fmamk_f32 v200, v155, 0x3a800000, v224
	v_fmamk_f32 v202, v192, 0x3a800000, v224
	v_fmamk_f32 v204, v193, 0x3a800000, v224
	v_fmamk_f32 v206, v194, 0x3a800000, v224
	v_fmamk_f32 v208, v195, 0x3a800000, v224
	v_fmamk_f32 v210, v196, 0x3a800000, v224
	v_fmamk_f32 v212, v197, 0x3a800000, v224
	v_fmamk_f32 v214, v198, 0x3a800000, v224
	v_rsq_f32_e32 v200, v200
	v_rsq_f32_e32 v202, v202
	v_rsq_f32_e32 v204, v204
	v_rsq_f32_e32 v206, v206
	v_rsq_f32_e32 v208, v208
	v_rsq_f32_e32 v210, v210
	v_rsq_f32_e32 v212, v212
	v_rsq_f32_e32 v214, v214
	v_pk_fma_f32 v[140:141], v[140:141], v[200:201], v[60:61] op_sel_hi:[1,0,1]
	v_pk_fma_f32 v[142:143], v[142:143], v[200:201], v[62:63] op_sel_hi:[1,0,1]
	v_pk_fma_f32 v[136:137], v[136:137], v[200:201], v[52:53] op_sel_hi:[1,0,1]
	v_pk_fma_f32 v[138:139], v[138:139], v[200:201], v[54:55] op_sel_hi:[1,0,1]
	v_pk_mul_f32 v[192:193], v[140:141], v[216:217] op_sel_hi:[1,0]
	v_pk_mul_f32 v[194:195], v[142:143], v[216:217] op_sel_hi:[1,0]
	v_pk_mul_f32 v[196:197], v[136:137], v[216:217] op_sel_hi:[1,0]
	v_pk_mul_f32 v[198:199], v[138:139], v[216:217] op_sel_hi:[1,0]
	v_pk_fma_f32 v[132:133], v[132:133], v[200:201], v[56:57] op_sel_hi:[1,0,1]
	v_pk_fma_f32 v[134:135], v[134:135], v[200:201], v[58:59] op_sel_hi:[1,0,1]
	v_pk_fma_f32 v[128:129], v[128:129], v[200:201], v[48:49] op_sel_hi:[1,0,1]
	v_pk_fma_f32 v[130:131], v[130:131], v[200:201], v[50:51] op_sel_hi:[1,0,1]
	v_exp_f32_e32 v192, v192
	v_exp_f32_e32 v193, v193
	v_exp_f32_e32 v194, v194
	v_exp_f32_e32 v195, v195
	v_exp_f32_e32 v196, v196
	v_exp_f32_e32 v197, v197
	v_exp_f32_e32 v198, v198
	v_exp_f32_e32 v199, v199
	v_pk_mul_f32 v[140:141], v[140:141], v[132:133]
	v_pk_mul_f32 v[142:143], v[142:143], v[134:135]
	v_pk_mul_f32 v[136:137], v[136:137], v[128:129]
	v_pk_mul_f32 v[138:139], v[138:139], v[130:131]
	v_pk_add_f32 v[192:193], v[192:193], 1.0 op_sel_hi:[1,0]
	v_pk_add_f32 v[194:195], v[194:195], 1.0 op_sel_hi:[1,0]
	v_pk_add_f32 v[196:197], v[196:197], 1.0 op_sel_hi:[1,0]
	v_pk_add_f32 v[198:199], v[198:199], 1.0 op_sel_hi:[1,0]
	v_rcp_f32_e32 v192, v192
	v_rcp_f32_e32 v193, v193
	v_rcp_f32_e32 v194, v194
	v_rcp_f32_e32 v195, v195
	v_rcp_f32_e32 v196, v196
	v_rcp_f32_e32 v197, v197
	v_rcp_f32_e32 v198, v198
	v_rcp_f32_e32 v199, v199
	v_pk_mul_f32 v[140:141], v[140:141], v[192:193]
	v_pk_mul_f32 v[142:143], v[142:143], v[194:195]
	v_pk_mul_f32 v[136:137], v[136:137], v[196:197]
	v_pk_mul_f32 v[138:139], v[138:139], v[198:199]
	v_cvt_pk_bf16_f32 v188, v140, v141
	v_cvt_pk_bf16_f32 v189, v142, v143
	v_cvt_pk_bf16_f32 v190, v136, v137
	v_cvt_pk_bf16_f32 v191, v138, v139
	global_store_dwordx4 v[178:179], v[188:191], off
	v_or_b32_e32 v186, 16, v154
	v_mad_i64_i32 v[186:187], s[0:1], v186, s99, v[158:159]
	v_lshl_add_u64 v[186:187], v[186:187], 0, v[176:177]
	v_pk_fma_f32 v[124:125], v[124:125], v[202:203], v[60:61] op_sel_hi:[1,0,1]
	v_pk_fma_f32 v[126:127], v[126:127], v[202:203], v[62:63] op_sel_hi:[1,0,1]
	v_pk_fma_f32 v[120:121], v[120:121], v[202:203], v[52:53] op_sel_hi:[1,0,1]
	v_pk_fma_f32 v[122:123], v[122:123], v[202:203], v[54:55] op_sel_hi:[1,0,1]
	v_pk_mul_f32 v[192:193], v[124:125], v[216:217] op_sel_hi:[1,0]
	v_pk_mul_f32 v[194:195], v[126:127], v[216:217] op_sel_hi:[1,0]
	v_pk_mul_f32 v[196:197], v[120:121], v[216:217] op_sel_hi:[1,0]
	v_pk_mul_f32 v[198:199], v[122:123], v[216:217] op_sel_hi:[1,0]
	v_pk_fma_f32 v[116:117], v[116:117], v[202:203], v[56:57] op_sel_hi:[1,0,1]
	v_pk_fma_f32 v[118:119], v[118:119], v[202:203], v[58:59] op_sel_hi:[1,0,1]
	v_pk_fma_f32 v[112:113], v[112:113], v[202:203], v[48:49] op_sel_hi:[1,0,1]
	v_pk_fma_f32 v[114:115], v[114:115], v[202:203], v[50:51] op_sel_hi:[1,0,1]
	v_exp_f32_e32 v192, v192
	v_exp_f32_e32 v193, v193
	v_exp_f32_e32 v194, v194
	v_exp_f32_e32 v195, v195
	v_exp_f32_e32 v196, v196
	v_exp_f32_e32 v197, v197
	v_exp_f32_e32 v198, v198
	v_exp_f32_e32 v199, v199
	v_pk_mul_f32 v[124:125], v[124:125], v[116:117]
	v_pk_mul_f32 v[126:127], v[126:127], v[118:119]
	v_pk_mul_f32 v[120:121], v[120:121], v[112:113]
	v_pk_mul_f32 v[122:123], v[122:123], v[114:115]
	v_pk_add_f32 v[192:193], v[192:193], 1.0 op_sel_hi:[1,0]
	v_pk_add_f32 v[194:195], v[194:195], 1.0 op_sel_hi:[1,0]
	v_pk_add_f32 v[196:197], v[196:197], 1.0 op_sel_hi:[1,0]
	v_pk_add_f32 v[198:199], v[198:199], 1.0 op_sel_hi:[1,0]
	v_rcp_f32_e32 v192, v192
	v_rcp_f32_e32 v193, v193
	v_rcp_f32_e32 v194, v194
	v_rcp_f32_e32 v195, v195
	v_rcp_f32_e32 v196, v196
	v_rcp_f32_e32 v197, v197
	v_rcp_f32_e32 v198, v198
	v_rcp_f32_e32 v199, v199
	v_pk_mul_f32 v[124:125], v[124:125], v[192:193]
	v_pk_mul_f32 v[126:127], v[126:127], v[194:195]
	v_pk_mul_f32 v[120:121], v[120:121], v[196:197]
	v_pk_mul_f32 v[122:123], v[122:123], v[198:199]
	v_cvt_pk_bf16_f32 v218, v124, v125
	v_cvt_pk_bf16_f32 v219, v126, v127
	v_cvt_pk_bf16_f32 v220, v120, v121
	v_cvt_pk_bf16_f32 v221, v122, v123
	global_store_dwordx4 v[186:187], v[218:221], off
	v_or_b32_e32 v186, 32, v154
	v_mad_i64_i32 v[186:187], s[0:1], v186, s99, v[158:159]
	v_lshl_add_u64 v[186:187], v[186:187], 0, v[176:177]
	v_pk_fma_f32 v[108:109], v[108:109], v[204:205], v[60:61] op_sel_hi:[1,0,1]
	v_pk_fma_f32 v[110:111], v[110:111], v[204:205], v[62:63] op_sel_hi:[1,0,1]
	v_pk_fma_f32 v[104:105], v[104:105], v[204:205], v[52:53] op_sel_hi:[1,0,1]
	v_pk_fma_f32 v[106:107], v[106:107], v[204:205], v[54:55] op_sel_hi:[1,0,1]
	v_pk_mul_f32 v[192:193], v[108:109], v[216:217] op_sel_hi:[1,0]
	v_pk_mul_f32 v[194:195], v[110:111], v[216:217] op_sel_hi:[1,0]
	v_pk_mul_f32 v[196:197], v[104:105], v[216:217] op_sel_hi:[1,0]
	v_pk_mul_f32 v[198:199], v[106:107], v[216:217] op_sel_hi:[1,0]
; __device__ __forceinline__ unsigned cvt_pk_bf16(float lo, float hi) { unsigned r; asm volatile("v_cvt_pk_bf16_f32 %0, %1, %2" : "=v"(r) : "v"(lo), "v"(hi)); return r; }
; __device__ __forceinline__ float silu_f(float g) { return g * __builtin_amdgcn_rcpf(1.0f + __expf(-g)); }
;     __device__ __forceinline__ void operator()(const f32x4 (&acc)[2][2][4][2], const Unit& u, int wr, int wc, int fr, int fq) const {
;     ...
;             for (int m = 0; m < 4; ++m) {
;                 const int row = row0 + ai * HALF + m * 16;
;                 const float rs = __builtin_amdgcn_rsqf(ssq[row] * (1.0f / 1024.0f) + 1e-6f);
;                 bf16_t* rowp = O + (size_t)row * 2816 + col0;
;                 const f32x4 g0 = acc[ai][0][m][0] * rs + sg0, g1 = acc[ai][0][m][1] * rs + sg1, u0 = acc[ai][1][m][0] * rs + su0, u1 = acc[ai][1][m][1] * rs + su1;
;                 u32x4 w;
;                 w.x = cvt_pk_bf16(silu_f(g0[0]) * u0[0], silu_f(g0[1]) * u0[1]);
;                 w.y = cvt_pk_bf16(silu_f(g0[2]) * u0[2], silu_f(g0[3]) * u0[3]);
;                 w.z = cvt_pk_bf16(silu_f(g1[0]) * u1[0], silu_f(g1[1]) * u1[1]);
;                 w.w = cvt_pk_bf16(silu_f(g1[2]) * u1[2], silu_f(g1[3]) * u1[3]);
;                 *(u32x4*)rowp = w;
	v_pk_fma_f32 v[100:101], v[100:101], v[204:205], v[56:57] op_sel_hi:[1,0,1]
	v_pk_fma_f32 v[102:103], v[102:103], v[204:205], v[58:59] op_sel_hi:[1,0,1]
	v_pk_fma_f32 v[96:97], v[96:97], v[204:205], v[48:49] op_sel_hi:[1,0,1]
	v_pk_fma_f32 v[98:99], v[98:99], v[204:205], v[50:51] op_sel_hi:[1,0,1]
	v_exp_f32_e32 v192, v192
	v_exp_f32_e32 v193, v193
	v_exp_f32_e32 v194, v194
	v_exp_f32_e32 v195, v195
	v_exp_f32_e32 v196, v196
	v_exp_f32_e32 v197, v197
	v_exp_f32_e32 v198, v198
	v_exp_f32_e32 v199, v199
	v_pk_mul_f32 v[108:109], v[108:109], v[100:101]
	v_pk_mul_f32 v[110:111], v[110:111], v[102:103]
	v_pk_mul_f32 v[104:105], v[104:105], v[96:97]
	v_pk_mul_f32 v[106:107], v[106:107], v[98:99]
	v_pk_add_f32 v[192:193], v[192:193], 1.0 op_sel_hi:[1,0]
	v_pk_add_f32 v[194:195], v[194:195], 1.0 op_sel_hi:[1,0]
	v_pk_add_f32 v[196:197], v[196:197], 1.0 op_sel_hi:[1,0]
	v_pk_add_f32 v[198:199], v[198:199], 1.0 op_sel_hi:[1,0]
	v_rcp_f32_e32 v192, v192
	v_rcp_f32_e32 v193, v193
	v_rcp_f32_e32 v194, v194
	v_rcp_f32_e32 v195, v195
	v_rcp_f32_e32 v196, v196
	v_rcp_f32_e32 v197, v197
	v_rcp_f32_e32 v198, v198
	v_rcp_f32_e32 v199, v199
	v_pk_mul_f32 v[108:109], v[108:109], v[192:193]
	v_pk_mul_f32 v[110:111], v[110:111], v[194:195]
	v_pk_mul_f32 v[104:105], v[104:105], v[196:197]
	v_pk_mul_f32 v[106:107], v[106:107], v[198:199]
	v_cvt_pk_bf16_f32 v188, v108, v109
	v_cvt_pk_bf16_f32 v189, v110, v111
	v_cvt_pk_bf16_f32 v190, v104, v105
	v_cvt_pk_bf16_f32 v191, v106, v107
	global_store_dwordx4 v[186:187], v[188:191], off
	v_or_b32_e32 v186, 48, v154
	v_mad_i64_i32 v[186:187], s[0:1], v186, s99, v[158:159]
	v_lshl_add_u64 v[186:187], v[186:187], 0, v[176:177]
	v_pk_fma_f32 v[92:93], v[92:93], v[206:207], v[60:61] op_sel_hi:[1,0,1]
	v_pk_fma_f32 v[94:95], v[94:95], v[206:207], v[62:63] op_sel_hi:[1,0,1]
	v_pk_fma_f32 v[88:89], v[88:89], v[206:207], v[52:53] op_sel_hi:[1,0,1]
	v_pk_fma_f32 v[90:91], v[90:91], v[206:207], v[54:55] op_sel_hi:[1,0,1]
	v_pk_mul_f32 v[192:193], v[92:93], v[216:217] op_sel_hi:[1,0]
	v_pk_mul_f32 v[194:195], v[94:95], v[216:217] op_sel_hi:[1,0]
	v_pk_mul_f32 v[196:197], v[88:89], v[216:217] op_sel_hi:[1,0]
	v_pk_mul_f32 v[198:199], v[90:91], v[216:217] op_sel_hi:[1,0]
	v_pk_fma_f32 v[84:85], v[84:85], v[206:207], v[56:57] op_sel_hi:[1,0,1]
	v_pk_fma_f32 v[86:87], v[86:87], v[206:207], v[58:59] op_sel_hi:[1,0,1]
	v_pk_fma_f32 v[80:81], v[80:81], v[206:207], v[48:49] op_sel_hi:[1,0,1]
	v_pk_fma_f32 v[82:83], v[82:83], v[206:207], v[50:51] op_sel_hi:[1,0,1]
	v_exp_f32_e32 v192, v192
	v_exp_f32_e32 v193, v193
	v_exp_f32_e32 v194, v194
	v_exp_f32_e32 v195, v195
	v_exp_f32_e32 v196, v196
	v_exp_f32_e32 v197, v197
	v_exp_f32_e32 v198, v198
	v_exp_f32_e32 v199, v199
	v_pk_mul_f32 v[92:93], v[92:93], v[84:85]
	v_pk_mul_f32 v[94:95], v[94:95], v[86:87]
	v_pk_mul_f32 v[88:89], v[88:89], v[80:81]
	v_pk_mul_f32 v[90:91], v[90:91], v[82:83]
	v_pk_add_f32 v[192:193], v[192:193], 1.0 op_sel_hi:[1,0]
	v_pk_add_f32 v[194:195], v[194:195], 1.0 op_sel_hi:[1,0]
	v_pk_add_f32 v[196:197], v[196:197], 1.0 op_sel_hi:[1,0]
	v_pk_add_f32 v[198:199], v[198:199], 1.0 op_sel_hi:[1,0]
	v_rcp_f32_e32 v192, v192
	v_rcp_f32_e32 v193, v193
	v_rcp_f32_e32 v194, v194
	v_rcp_f32_e32 v195, v195
	v_rcp_f32_e32 v196, v196
	v_rcp_f32_e32 v197, v197
	v_rcp_f32_e32 v198, v198
	v_rcp_f32_e32 v199, v199
	v_pk_mul_f32 v[92:93], v[92:93], v[192:193]
	v_pk_mul_f32 v[94:95], v[94:95], v[194:195]
	v_pk_mul_f32 v[88:89], v[88:89], v[196:197]
	v_pk_mul_f32 v[90:91], v[90:91], v[198:199]
	v_cvt_pk_bf16_f32 v218, v92, v93
	v_cvt_pk_bf16_f32 v219, v94, v95
	v_cvt_pk_bf16_f32 v220, v88, v89
	v_cvt_pk_bf16_f32 v221, v90, v91
	global_store_dwordx4 v[186:187], v[218:221], off
	v_add_u32_e32 v186, 0x80, v154
	v_mad_i64_i32 v[186:187], s[0:1], v186, s99, v[158:159]
	v_lshl_add_u64 v[186:187], v[186:187], 0, v[176:177]
	v_pk_fma_f32 v[76:77], v[76:77], v[208:209], v[60:61] op_sel_hi:[1,0,1]
	v_pk_fma_f32 v[78:79], v[78:79], v[208:209], v[62:63] op_sel_hi:[1,0,1]
	v_pk_fma_f32 v[72:73], v[72:73], v[208:209], v[52:53] op_sel_hi:[1,0,1]
	v_pk_fma_f32 v[74:75], v[74:75], v[208:209], v[54:55] op_sel_hi:[1,0,1]
	v_pk_mul_f32 v[192:193], v[76:77], v[216:217] op_sel_hi:[1,0]
	v_pk_mul_f32 v[194:195], v[78:79], v[216:217] op_sel_hi:[1,0]
	v_pk_mul_f32 v[196:197], v[72:73], v[216:217] op_sel_hi:[1,0]
	v_pk_mul_f32 v[198:199], v[74:75], v[216:217] op_sel_hi:[1,0]
	v_pk_fma_f32 v[68:69], v[68:69], v[208:209], v[56:57] op_sel_hi:[1,0,1]
	v_pk_fma_f32 v[70:71], v[70:71], v[208:209], v[58:59] op_sel_hi:[1,0,1]
	v_pk_fma_f32 v[64:65], v[64:65], v[208:209], v[48:49] op_sel_hi:[1,0,1]
	v_pk_fma_f32 v[66:67], v[66:67], v[208:209], v[50:51] op_sel_hi:[1,0,1]
	v_exp_f32_e32 v192, v192
	v_exp_f32_e32 v193, v193
	v_exp_f32_e32 v194, v194
	v_exp_f32_e32 v195, v195
	v_exp_f32_e32 v196, v196
	v_exp_f32_e32 v197, v197
	v_exp_f32_e32 v198, v198
	v_exp_f32_e32 v199, v199
	v_pk_mul_f32 v[76:77], v[76:77], v[68:69]
	v_pk_mul_f32 v[78:79], v[78:79], v[70:71]
	v_pk_mul_f32 v[72:73], v[72:73], v[64:65]
	v_pk_mul_f32 v[74:75], v[74:75], v[66:67]
	v_pk_add_f32 v[192:193], v[192:193], 1.0 op_sel_hi:[1,0]
	v_pk_add_f32 v[194:195], v[194:195], 1.0 op_sel_hi:[1,0]
	v_pk_add_f32 v[196:197], v[196:197], 1.0 op_sel_hi:[1,0]
	v_pk_add_f32 v[198:199], v[198:199], 1.0 op_sel_hi:[1,0]
	v_rcp_f32_e32 v192, v192
	v_rcp_f32_e32 v193, v193
	v_rcp_f32_e32 v194, v194
	v_rcp_f32_e32 v195, v195
	v_rcp_f32_e32 v196, v196
	v_rcp_f32_e32 v197, v197
	v_rcp_f32_e32 v198, v198
	v_rcp_f32_e32 v199, v199
	v_pk_mul_f32 v[76:77], v[76:77], v[192:193]
	v_pk_mul_f32 v[78:79], v[78:79], v[194:195]
	v_pk_mul_f32 v[72:73], v[72:73], v[196:197]
; __device__ __forceinline__ unsigned cvt_pk_bf16(float lo, float hi) { unsigned r; asm volatile("v_cvt_pk_bf16_f32 %0, %1, %2" : "=v"(r) : "v"(lo), "v"(hi)); return r; }
; #define PG8_BAR __builtin_amdgcn_s_barrier()
; __device__ __forceinline__ float silu_f(float g) { return g * __builtin_amdgcn_rcpf(1.0f + __expf(-g)); }
; template <class Epi, class Sched, bool ALIGN_EPI = false, bool SP2 = false>
; __device__ __forceinline__ void gemm_phase(PG8_LAS unsigned char* lds, const Gemm g, const Sched& S, const Epi& E, const int tid_in) {
;     ...
;         if (!has_next) break;
; #pragma unroll
;         for (int a = 0; a < 2; ++a)
; #pragma unroll
;             for (int b = 0; b < 2; ++b)
; #pragma unroll
;                 for (int m = 0; m < 4; ++m)
; #pragma unroll
;                     for (int n = 0; n < 2; ++n) acc[a][b][m][n] = (f32x4){0.f, 0.f, 0.f, 0.f};
;         cur = nxt; cA = nA; cB = nB; ++ui;
;         if constexpr (ALIGN_EPI) { if (wr == 1) PG8_BAR; }
;     __device__ __forceinline__ void operator()(const f32x4 (&acc)[2][2][4][2], const Unit& u, int wr, int wc, int fr, int fq) const {
;     ...
;             for (int m = 0; m < 4; ++m) {
;                 const int row = row0 + ai * HALF + m * 16;
;                 const float rs = __builtin_amdgcn_rsqf(ssq[row] * (1.0f / 1024.0f) + 1e-6f);
;                 bf16_t* rowp = O + (size_t)row * 2816 + col0;
;                 const f32x4 g0 = acc[ai][0][m][0] * rs + sg0, g1 = acc[ai][0][m][1] * rs + sg1, u0 = acc[ai][1][m][0] * rs + su0, u1 = acc[ai][1][m][1] * rs + su1;
;                 u32x4 w;
;                 w.x = cvt_pk_bf16(silu_f(g0[0]) * u0[0], silu_f(g0[1]) * u0[1]);
;                 w.y = cvt_pk_bf16(silu_f(g0[2]) * u0[2], silu_f(g0[3]) * u0[3]);
;                 w.z = cvt_pk_bf16(silu_f(g1[0]) * u1[0], silu_f(g1[1]) * u1[1]);
;                 w.w = cvt_pk_bf16(silu_f(g1[2]) * u1[2], silu_f(g1[3]) * u1[3]);
;                 *(u32x4*)rowp = w;
	v_pk_mul_f32 v[74:75], v[74:75], v[198:199]
	v_cvt_pk_bf16_f32 v188, v76, v77
	v_cvt_pk_bf16_f32 v189, v78, v79
	v_cvt_pk_bf16_f32 v190, v72, v73
	v_cvt_pk_bf16_f32 v191, v74, v75
	global_store_dwordx4 v[186:187], v[188:191], off
	v_add_u32_e32 v186, 0x90, v154
	v_mad_i64_i32 v[186:187], s[0:1], v186, s99, v[158:159]
	v_lshl_add_u64 v[186:187], v[186:187], 0, v[176:177]
	v_pk_fma_f32 v[44:45], v[44:45], v[210:211], v[60:61] op_sel_hi:[1,0,1]
	v_pk_fma_f32 v[46:47], v[46:47], v[210:211], v[62:63] op_sel_hi:[1,0,1]
	v_pk_fma_f32 v[40:41], v[40:41], v[210:211], v[52:53] op_sel_hi:[1,0,1]
	v_pk_fma_f32 v[42:43], v[42:43], v[210:211], v[54:55] op_sel_hi:[1,0,1]
	v_pk_mul_f32 v[192:193], v[44:45], v[216:217] op_sel_hi:[1,0]
	v_pk_mul_f32 v[194:195], v[46:47], v[216:217] op_sel_hi:[1,0]
	v_pk_mul_f32 v[196:197], v[40:41], v[216:217] op_sel_hi:[1,0]
	v_pk_mul_f32 v[198:199], v[42:43], v[216:217] op_sel_hi:[1,0]
	v_pk_fma_f32 v[36:37], v[36:37], v[210:211], v[56:57] op_sel_hi:[1,0,1]
	v_pk_fma_f32 v[38:39], v[38:39], v[210:211], v[58:59] op_sel_hi:[1,0,1]
	v_pk_fma_f32 v[32:33], v[32:33], v[210:211], v[48:49] op_sel_hi:[1,0,1]
	v_pk_fma_f32 v[34:35], v[34:35], v[210:211], v[50:51] op_sel_hi:[1,0,1]
	v_exp_f32_e32 v192, v192
	v_exp_f32_e32 v193, v193
	v_exp_f32_e32 v194, v194
	v_exp_f32_e32 v195, v195
	v_exp_f32_e32 v196, v196
	v_exp_f32_e32 v197, v197
	v_exp_f32_e32 v198, v198
	v_exp_f32_e32 v199, v199
	v_pk_mul_f32 v[44:45], v[44:45], v[36:37]
	v_pk_mul_f32 v[46:47], v[46:47], v[38:39]
	v_pk_mul_f32 v[40:41], v[40:41], v[32:33]
	v_pk_mul_f32 v[42:43], v[42:43], v[34:35]
	v_pk_add_f32 v[192:193], v[192:193], 1.0 op_sel_hi:[1,0]
	v_pk_add_f32 v[194:195], v[194:195], 1.0 op_sel_hi:[1,0]
	v_pk_add_f32 v[196:197], v[196:197], 1.0 op_sel_hi:[1,0]
	v_pk_add_f32 v[198:199], v[198:199], 1.0 op_sel_hi:[1,0]
	v_rcp_f32_e32 v192, v192
	v_rcp_f32_e32 v193, v193
	v_rcp_f32_e32 v194, v194
	v_rcp_f32_e32 v195, v195
	v_rcp_f32_e32 v196, v196
	v_rcp_f32_e32 v197, v197
	v_rcp_f32_e32 v198, v198
	v_rcp_f32_e32 v199, v199
	v_pk_mul_f32 v[44:45], v[44:45], v[192:193]
	v_pk_mul_f32 v[46:47], v[46:47], v[194:195]
	v_pk_mul_f32 v[40:41], v[40:41], v[196:197]
	v_pk_mul_f32 v[42:43], v[42:43], v[198:199]
	v_cvt_pk_bf16_f32 v218, v44, v45
	v_cvt_pk_bf16_f32 v219, v46, v47
	v_cvt_pk_bf16_f32 v220, v40, v41
	v_cvt_pk_bf16_f32 v221, v42, v43
	global_store_dwordx4 v[186:187], v[218:221], off
	v_add_u32_e32 v186, 0xa0, v154
	v_mad_i64_i32 v[186:187], s[0:1], v186, s99, v[158:159]
	v_lshl_add_u64 v[186:187], v[186:187], 0, v[176:177]
	v_pk_fma_f32 v[28:29], v[28:29], v[212:213], v[60:61] op_sel_hi:[1,0,1]
	v_pk_fma_f32 v[30:31], v[30:31], v[212:213], v[62:63] op_sel_hi:[1,0,1]
	v_pk_fma_f32 v[24:25], v[24:25], v[212:213], v[52:53] op_sel_hi:[1,0,1]
	v_pk_fma_f32 v[26:27], v[26:27], v[212:213], v[54:55] op_sel_hi:[1,0,1]
	v_pk_mul_f32 v[192:193], v[28:29], v[216:217] op_sel_hi:[1,0]
	v_pk_mul_f32 v[194:195], v[30:31], v[216:217] op_sel_hi:[1,0]
	v_pk_mul_f32 v[196:197], v[24:25], v[216:217] op_sel_hi:[1,0]
	v_pk_mul_f32 v[198:199], v[26:27], v[216:217] op_sel_hi:[1,0]
	v_pk_fma_f32 v[20:21], v[20:21], v[212:213], v[56:57] op_sel_hi:[1,0,1]
	v_pk_fma_f32 v[22:23], v[22:23], v[212:213], v[58:59] op_sel_hi:[1,0,1]
	v_pk_fma_f32 v[16:17], v[16:17], v[212:213], v[48:49] op_sel_hi:[1,0,1]
	v_pk_fma_f32 v[18:19], v[18:19], v[212:213], v[50:51] op_sel_hi:[1,0,1]
	v_exp_f32_e32 v192, v192
	v_exp_f32_e32 v193, v193
	v_exp_f32_e32 v194, v194
	v_exp_f32_e32 v195, v195
	v_exp_f32_e32 v196, v196
	v_exp_f32_e32 v197, v197
	v_exp_f32_e32 v198, v198
	v_exp_f32_e32 v199, v199
	v_pk_mul_f32 v[28:29], v[28:29], v[20:21]
	v_pk_mul_f32 v[30:31], v[30:31], v[22:23]
	v_pk_mul_f32 v[24:25], v[24:25], v[16:17]
	v_pk_mul_f32 v[26:27], v[26:27], v[18:19]
	v_pk_add_f32 v[192:193], v[192:193], 1.0 op_sel_hi:[1,0]
	v_pk_add_f32 v[194:195], v[194:195], 1.0 op_sel_hi:[1,0]
	v_pk_add_f32 v[196:197], v[196:197], 1.0 op_sel_hi:[1,0]
	v_pk_add_f32 v[198:199], v[198:199], 1.0 op_sel_hi:[1,0]
	v_rcp_f32_e32 v192, v192
	v_rcp_f32_e32 v193, v193
	v_rcp_f32_e32 v194, v194
	v_rcp_f32_e32 v195, v195
	v_rcp_f32_e32 v196, v196
	v_rcp_f32_e32 v197, v197
	v_rcp_f32_e32 v198, v198
	v_rcp_f32_e32 v199, v199
	v_pk_mul_f32 v[28:29], v[28:29], v[192:193]
	v_pk_mul_f32 v[30:31], v[30:31], v[194:195]
	v_pk_mul_f32 v[24:25], v[24:25], v[196:197]
	v_pk_mul_f32 v[26:27], v[26:27], v[198:199]
	v_cvt_pk_bf16_f32 v188, v28, v29
	v_cvt_pk_bf16_f32 v189, v30, v31
	v_cvt_pk_bf16_f32 v190, v24, v25
	v_cvt_pk_bf16_f32 v191, v26, v27
	global_store_dwordx4 v[186:187], v[188:191], off
	v_add_u32_e32 v186, 0xb0, v154
	v_mad_i64_i32 v[186:187], s[0:1], v186, s99, v[158:159]
	v_lshl_add_u64 v[186:187], v[186:187], 0, v[176:177]
	v_pk_fma_f32 v[12:13], v[12:13], v[214:215], v[60:61] op_sel_hi:[1,0,1]
	v_pk_fma_f32 v[14:15], v[14:15], v[214:215], v[62:63] op_sel_hi:[1,0,1]
	v_pk_fma_f32 v[8:9], v[8:9], v[214:215], v[52:53] op_sel_hi:[1,0,1]
	v_pk_fma_f32 v[10:11], v[10:11], v[214:215], v[54:55] op_sel_hi:[1,0,1]
	v_pk_mul_f32 v[192:193], v[12:13], v[216:217] op_sel_hi:[1,0]
	v_pk_mul_f32 v[194:195], v[14:15], v[216:217] op_sel_hi:[1,0]
	v_pk_mul_f32 v[196:197], v[8:9], v[216:217] op_sel_hi:[1,0]
	v_pk_mul_f32 v[198:199], v[10:11], v[216:217] op_sel_hi:[1,0]
	v_pk_fma_f32 v[4:5], v[4:5], v[214:215], v[56:57] op_sel_hi:[1,0,1]
	v_pk_fma_f32 v[6:7], v[6:7], v[214:215], v[58:59] op_sel_hi:[1,0,1]
	v_pk_fma_f32 v[0:1], v[0:1], v[214:215], v[48:49] op_sel_hi:[1,0,1]
	v_pk_fma_f32 v[2:3], v[2:3], v[214:215], v[50:51] op_sel_hi:[1,0,1]
	v_exp_f32_e32 v192, v192
	v_exp_f32_e32 v193, v193
	v_exp_f32_e32 v194, v194
	v_exp_f32_e32 v195, v195
	v_exp_f32_e32 v196, v196
	v_exp_f32_e32 v197, v197
	v_exp_f32_e32 v198, v198
	v_exp_f32_e32 v199, v199
	v_pk_mul_f32 v[12:13], v[12:13], v[4:5]
	v_pk_mul_f32 v[14:15], v[14:15], v[6:7]
	v_pk_mul_f32 v[8:9], v[8:9], v[0:1]
	v_pk_mul_f32 v[10:11], v[10:11], v[2:3]
	v_pk_add_f32 v[192:193], v[192:193], 1.0 op_sel_hi:[1,0]
	v_pk_add_f32 v[194:195], v[194:195], 1.0 op_sel_hi:[1,0]
	v_pk_add_f32 v[196:197], v[196:197], 1.0 op_sel_hi:[1,0]
	v_pk_add_f32 v[198:199], v[198:199], 1.0 op_sel_hi:[1,0]
	v_rcp_f32_e32 v192, v192
	v_rcp_f32_e32 v193, v193
	v_rcp_f32_e32 v194, v194
	v_rcp_f32_e32 v195, v195
	v_rcp_f32_e32 v196, v196
	v_rcp_f32_e32 v197, v197
	v_rcp_f32_e32 v198, v198
	v_rcp_f32_e32 v199, v199
	v_pk_mul_f32 v[12:13], v[12:13], v[192:193]
	v_pk_mul_f32 v[14:15], v[14:15], v[194:195]
	v_pk_mul_f32 v[8:9], v[8:9], v[196:197]
	v_pk_mul_f32 v[10:11], v[10:11], v[198:199]
	v_cvt_pk_bf16_f32 v218, v12, v13
	v_cvt_pk_bf16_f32 v219, v14, v15
	v_cvt_pk_bf16_f32 v220, v8, v9
	v_cvt_pk_bf16_f32 v221, v10, v11
	global_store_dwordx4 v[186:187], v[218:221], off
	s_mov_b32 s100, 1
	s_cbranch_vccnz .LBB0_396
	s_andn2_b64 vcc, exec, s[34:35]
	s_cbranch_vccnz .LBB0_395
	s_barrier
	s_branch .LBB0_395

; #define LAS __attribute__((address_space(3)))
; __global__ void __launch_bounds__(512, 2) fwd_kernel(Params p) {
;     extern __shared__ __attribute__((aligned(16))) unsigned char lds_raw[];
;     LAS unsigned char* lds = (LAS unsigned char*)lds_raw;
;     volatile LAS unsigned* bst = (volatile LAS unsigned*)(lds + NA_END + 64);
;     if (threadIdx.x < 4) bst[threadIdx.x] = 0u;
;     __syncthreads();
;     XcdBarrier bar = xcd_barrier_post((unsigned*)(p.ws + WS_CTL) + CW_BAR, bst);
	.amdhsa_kernel _Z10fwd_kernel6Params
		.amdhsa_group_segment_fixed_size 0
		.amdhsa_private_segment_fixed_size 0
		.amdhsa_kernarg_size 424
		.amdhsa_user_sgpr_count 2
		.amdhsa_user_sgpr_dispatch_ptr 0
		.amdhsa_user_sgpr_queue_ptr 0
		.amdhsa_user_sgpr_kernarg_segment_ptr 1
		.amdhsa_user_sgpr_dispatch_id 0
		.amdhsa_user_sgpr_kernarg_preload_length 0
		.amdhsa_user_sgpr_kernarg_preload_offset 0
		.amdhsa_user_sgpr_private_segment_size 0
		.amdhsa_uses_dynamic_stack 0
		.amdhsa_enable_private_segment 0
		.amdhsa_system_sgpr_workgroup_id_x 1
		.amdhsa_system_sgpr_workgroup_id_y 0
		.amdhsa_system_sgpr_workgroup_id_z 0
		.amdhsa_system_sgpr_workgroup_info 0
		.amdhsa_system_vgpr_workitem_id 2
		.amdhsa_next_free_vgpr 256
		.amdhsa_next_free_sgpr 102
		.amdhsa_accum_offset 256
		.amdhsa_reserve_vcc 1
		.amdhsa_float_round_mode_32 0
		.amdhsa_float_round_mode_16_64 0
		.amdhsa_float_denorm_mode_32 3
		.amdhsa_float_denorm_mode_16_64 3
		.amdhsa_dx10_clamp 1
		.amdhsa_ieee_mode 1
		.amdhsa_fp16_overflow 0
		.amdhsa_tg_split 0
		.amdhsa_exception_fp_ieee_invalid_op 0
		.amdhsa_exception_fp_denorm_src 0
		.amdhsa_exception_fp_ieee_div_zero 0
		.amdhsa_exception_fp_ieee_overflow 0
		.amdhsa_exception_fp_ieee_underflow 0
		.amdhsa_exception_fp_ieee_inexact 0
		.amdhsa_exception_int_div_zero 0
	.end_amdhsa_kernel

; #define LAS __attribute__((address_space(3)))
; __global__ void __launch_bounds__(512, 2) fwd_kernel(Params p) {
;     extern __shared__ __attribute__((aligned(16))) unsigned char lds_raw[];
;     LAS unsigned char* lds = (LAS unsigned char*)lds_raw;
;     volatile LAS unsigned* bst = (volatile LAS unsigned*)(lds + NA_END + 64);
;     if (threadIdx.x < 4) bst[threadIdx.x] = 0u;
;     __syncthreads();
;     XcdBarrier bar = xcd_barrier_post((unsigned*)(p.ws + WS_CTL) + CW_BAR, bst);
amdhsa.kernels:
  - .agpr_count:     0
    .args:
      - .offset:         0
        .size:           168
        .value_kind:     by_value
      - .offset:         168
        .size:           4
        .value_kind:     hidden_block_count_x
      - .offset:         172
        .size:           4
        .value_kind:     hidden_block_count_y
      - .offset:         176
        .size:           4
        .value_kind:     hidden_block_count_z
      - .offset:         180
        .size:           2
        .value_kind:     hidden_group_size_x
      - .offset:         182
        .size:           2
        .value_kind:     hidden_group_size_y
      - .offset:         184
        .size:           2
        .value_kind:     hidden_group_size_z
      - .offset:         186
        .size:           2
        .value_kind:     hidden_remainder_x
      - .offset:         188
        .size:           2
        .value_kind:     hidden_remainder_y
      - .offset:         190
        .size:           2
        .value_kind:     hidden_remainder_z
      - .offset:         208
        .size:           8
        .value_kind:     hidden_global_offset_x
      - .offset:         216
        .size:           8
        .value_kind:     hidden_global_offset_y
      - .offset:         224
        .size:           8
        .value_kind:     hidden_global_offset_z
      - .offset:         232
        .size:           2
        .value_kind:     hidden_grid_dims
      - .offset:         256
        .size:           8
        .value_kind:     hidden_multigrid_sync_arg
      - .offset:         288
        .size:           4
        .value_kind:     hidden_dynamic_lds_size
    .group_segment_fixed_size: 0
    .kernarg_segment_align: 8
    .kernarg_segment_size: 424
    .language:       OpenCL C
    .language_version:
      - 2
      - 0
    .max_flat_workgroup_size: 512
    .name:           _Z10fwd_kernel6Params
    .private_segment_fixed_size: 0
    .sgpr_count:     108
    .sgpr_spill_count: 199
    .symbol:         _Z10fwd_kernel6Params.kd
    .uniform_work_group_size: 1
    .uses_dynamic_stack: false
    .vgpr_count:     256
    .vgpr_spill_count: 0
    .wavefront_size: 64
